# out-projection (layer 0) epilogues: gate loads issued 4 at a time and waited once per group
# speedup vs baseline: 1.0041x; 1.0041x over previous
; DI f32x16 mfma32(bf16x8 a, bf16x8 b, f32x16 c) { return __builtin_amdgcn_mfma_f32_32x32x16_bf16(a, b, c, 0, 0, 0); }
; DI s16x4 tr_read(const char* p) { bfx4 r = __builtin_amdgcn_ds_read_tr16_b64_v4bf16((LDS_AS bfx4*)p); return __builtin_bit_cast(s16x4, r); }
; DI bf16x8 cat8(s16x4 lo, s16x4 hi) { return __builtin_shufflevector(lo, hi, 0, 1, 2, 3, 4, 5, 6, 7); }
; template <int BM, class Epi>
; DI void gemm_tile(const bf16_t* __restrict__ A, int lda, const bf16_t* __restrict__ B, int ldb, int K, int row0, int col0, const Epi& epi, char* smem) {
;     ...
;     for (int kt = 0; kt < nk; ++kt) {
;         const char* cur = smem + (kt & 1) * GSTAGE;
;         char* nxt = smem + ((kt & 1) ^ 1) * GSTAGE;
;         const bool w1 = kt + 1 < nk, l2 = kt + 2 < nk;
;         const bf16_t* a2 = ag + (size_t)(kt + 2) * 64; const bf16_t* b2 = bg + (size_t)(kt + 2) * 64 * ldb;
; #pragma unroll
;         for (int s = 0; s < 4; ++s) {
;             bf16x8 xf[MI], wf[2];
; #pragma unroll
;             for (int mi = 0; mi < MI; ++mi) xf[mi] = *(const bf16x8*)(cur + xoff + mi * 32 * GA_S + s * 32);
; #pragma unroll
;             for (int ni = 0; ni < 2; ++ni) {
;                 const char* wp = cur + woff + s * 16 * GB_S + ni * 64;
;                 wf[ni] = cat8(tr_read(wp), tr_read(wp + 4 * GB_S));
;             }
; #pragma unroll
;             for (int mi = 0; mi < MI; ++mi)
; #pragma unroll
;                 for (int ni = 0; ni < 2; ++ni) acc[mi][ni] = mfma32(wf[ni], xf[mi], acc[mi][ni]);
;             if (w1) {
;                 if (s < NA_) *(u32x4*)(nxt + aw + 64 * s * GA_S) = ra[s];
;                 *(u32x4*)(nxt + bw + 16 * s * GB_S) = rb[s];
;             }
;             if (l2) {
;                 if (s < NA_) ra[s] = *(const u32x4*)(a2 + (size_t)(64 * s) * lda);
;                 rb[s] = *(const u32x4*)(b2 + (size_t)(16 * s) * ldb);
;             }
;         }
;         __syncthreads();
;     }
.LBB0_76:
	s_and_b32 s0, s11, 1
	s_mul_i32 s1, s0, 0x12000
	s_add_i32 s1, s1, 0
	v_add3_u32 v172, s1, v175, v176
	v_add3_u32 v163, s1, v165, v174
	ds_read_b64_tr_b16 v[180:181], v172 offset:36864
	ds_read_b64_tr_b16 v[182:183], v172 offset:39168
	ds_read_b128 v[184:187], v163
	ds_read_b128 v[188:191], v163 offset:4608
	ds_read_b64_tr_b16 v[220:221], v172 offset:39232
	ds_read_b64_tr_b16 v[218:219], v172 offset:36928
	s_xor_b32 s0, s0, 1
	s_mul_i32 s0, s0, 0x12000
	s_add_i32 s0, s0, 0
	v_add_u32_e32 v179, s0, v164
	s_waitcnt lgkmcnt(3)
	v_mfma_f32_32x32x16_bf16 v[112:127], v[180:183], v[184:187], v[112:127]
	v_add_u32_e32 v217, s0, v178
	s_add_i32 s11, s11, 1
	s_cmp_eq_u32 s11, 14
	s_waitcnt lgkmcnt(0)
	v_mfma_f32_32x32x16_bf16 v[96:111], v[218:221], v[184:187], v[96:111]
	v_mfma_f32_32x32x16_bf16 v[80:95], v[180:183], v[188:191], v[80:95]
	v_mfma_f32_32x32x16_bf16 v[64:79], v[218:221], v[188:191], v[64:79]
	ds_read_b128 v[184:187], v163 offset:9216
	ds_read_b128 v[188:191], v163 offset:13824
	s_waitcnt vmcnt(7)
	ds_write_b128 v179, v[152:155]
	s_waitcnt vmcnt(3)
	ds_write_b128 v217, v[156:159] offset:36864
	ds_read_b64_tr_b16 v[152:153], v172 offset:46080
	s_waitcnt lgkmcnt(4)
	v_mfma_f32_32x32x16_bf16 v[48:63], v[180:183], v[184:187], v[48:63]
	v_mfma_f32_32x32x16_bf16 v[32:47], v[218:221], v[184:187], v[32:47]
	s_waitcnt lgkmcnt(3)
	v_mfma_f32_32x32x16_bf16 v[16:31], v[180:183], v[188:191], v[16:31]
	ds_read_b64_tr_b16 v[154:155], v172 offset:48384
	ds_read_b128 v[156:159], v163 offset:32
	ds_read_b128 v[180:183], v163 offset:4640
	ds_read_b64_tr_b16 v[186:187], v172 offset:48448
	ds_read_b64_tr_b16 v[184:185], v172 offset:46144
	s_waitcnt lgkmcnt(3)
	v_mfma_f32_32x32x16_bf16 v[112:127], v[152:155], v[156:159], v[112:127]
	s_waitcnt lgkmcnt(0)
	v_mfma_f32_32x32x16_bf16 v[96:111], v[184:187], v[156:159], v[96:111]
	v_mfma_f32_32x32x16_bf16 v[80:95], v[152:155], v[180:183], v[80:95]
	v_mfma_f32_32x32x16_bf16 v[64:79], v[184:187], v[180:183], v[64:79]
	ds_read_b128 v[156:159], v163 offset:9248
	ds_read_b128 v[180:183], v163 offset:13856
	ds_write_b128 v179, v[144:147] offset:9216
	s_waitcnt vmcnt(2)
	ds_write_b128 v217, v[148:151] offset:46080
	ds_read_b64_tr_b16 v[144:145], v172 offset:55296
	s_waitcnt lgkmcnt(4)
	v_mfma_f32_32x32x16_bf16 v[48:63], v[152:155], v[156:159], v[48:63]
	v_mfma_f32_32x32x16_bf16 v[32:47], v[184:187], v[156:159], v[32:47]
	s_waitcnt lgkmcnt(3)
	v_mfma_f32_32x32x16_bf16 v[16:31], v[152:155], v[180:183], v[16:31]
	ds_read_b64_tr_b16 v[146:147], v172 offset:57600
	ds_read_b128 v[148:151], v163 offset:64
	ds_read_b128 v[152:155], v163 offset:4672
	ds_read_b64_tr_b16 v[158:159], v172 offset:57664
	ds_read_b64_tr_b16 v[156:157], v172 offset:55360
	v_mfma_f32_32x32x16_bf16 v[0:15], v[218:221], v[188:191], v[0:15]
	s_waitcnt lgkmcnt(3)
	v_mfma_f32_32x32x16_bf16 v[112:127], v[144:147], v[148:151], v[112:127]
	s_waitcnt lgkmcnt(0)
	v_mfma_f32_32x32x16_bf16 v[96:111], v[156:159], v[148:151], v[96:111]
	v_mfma_f32_32x32x16_bf16 v[80:95], v[144:147], v[152:155], v[80:95]
	v_mfma_f32_32x32x16_bf16 v[64:79], v[156:159], v[152:155], v[64:79]
	ds_read_b128 v[148:151], v163 offset:9280
	ds_read_b128 v[152:155], v163 offset:13888
	ds_write_b128 v179, v[136:139] offset:18432
	s_waitcnt vmcnt(1)
	ds_write_b128 v217, v[140:143] offset:55296
	s_waitcnt lgkmcnt(3)
	v_mfma_f32_32x32x16_bf16 v[48:63], v[144:147], v[148:151], v[48:63]
	v_mfma_f32_32x32x16_bf16 v[32:47], v[156:159], v[148:151], v[32:47]
	v_add_u32_e32 v148, 0x9000, v172
	s_waitcnt lgkmcnt(2)
	v_mfma_f32_32x32x16_bf16 v[16:31], v[144:147], v[152:155], v[16:31]
	v_lshl_add_u64 v[144:145], s[94:95], 0, v[160:161]
	v_lshl_add_u64 v[146:147], s[94:95], 0, v[166:167]
	v_lshl_add_u64 v[166:167], v[166:167], 0, s[24:25]
	v_lshl_add_u64 v[160:161], v[160:161], 0, s[22:23]
	v_mfma_f32_32x32x16_bf16 v[0:15], v[184:187], v[180:183], v[0:15]
	ds_read_b64_tr_b16 v[180:181], v172 offset:64512
	ds_read_b64_tr_b16 v[182:183], v148 offset:29952
	ds_read_b128 v[136:139], v163 offset:96
	ds_read_b128 v[140:143], v163 offset:4704
	ds_read_b64_tr_b16 v[186:187], v148 offset:30016
	ds_read_b64_tr_b16 v[184:185], v172 offset:64576
	v_add_co_u32_e32 v148, vcc, s14, v144
	s_nop 1
	v_addc_co_u32_e32 v149, vcc, 0, v145, vcc
	v_add_co_u32_e32 v150, vcc, s17, v146
	s_waitcnt lgkmcnt(3)
	v_mfma_f32_32x32x16_bf16 v[112:127], v[180:183], v[136:139], v[112:127]
	v_addc_co_u32_e32 v151, vcc, 0, v147, vcc
	v_add_co_u32_e32 v192, vcc, s15, v144
	s_nop 1
	v_addc_co_u32_e32 v193, vcc, 0, v145, vcc
	v_add_co_u32_e32 v218, vcc, s16, v146
	s_waitcnt lgkmcnt(0)
	v_mfma_f32_32x32x16_bf16 v[96:111], v[184:187], v[136:139], v[96:111]
	v_addc_co_u32_e32 v219, vcc, 0, v147, vcc
	v_add_co_u32_e32 v220, vcc, s18, v144
	ds_read_b128 v[136:139], v163 offset:9312
	ds_read_b128 v[188:191], v163 offset:13920
	v_addc_co_u32_e32 v221, vcc, 0, v145, vcc
	v_add_co_u32_e32 v222, vcc, s19, v146
	v_mfma_f32_32x32x16_bf16 v[0:15], v[156:159], v[152:155], v[0:15]
	s_nop 0
	v_addc_co_u32_e32 v223, vcc, 0, v147, vcc
	v_add_co_u32_e32 v224, vcc, s20, v144
	global_load_dwordx4 v[152:155], v[148:149], off offset:768
	global_load_dwordx4 v[156:159], v[150:151], off
	v_addc_co_u32_e32 v225, vcc, 0, v145, vcc
	v_add_co_u32_e32 v226, vcc, s21, v146
	v_mfma_f32_32x32x16_bf16 v[80:95], v[180:183], v[140:143], v[80:95]
	s_nop 0
	v_addc_co_u32_e32 v227, vcc, 0, v147, vcc
	v_mfma_f32_32x32x16_bf16 v[64:79], v[184:187], v[140:143], v[64:79]
	s_waitcnt lgkmcnt(1)
	v_mfma_f32_32x32x16_bf16 v[48:63], v[180:183], v[136:139], v[48:63]
	v_mfma_f32_32x32x16_bf16 v[32:47], v[184:187], v[136:139], v[32:47]
	global_load_dwordx4 v[144:147], v[192:193], off offset:768
	global_load_dwordx4 v[148:151], v[218:219], off
	global_load_dwordx4 v[136:139], v[220:221], off offset:768
	global_load_dwordx4 v[140:143], v[222:223], off
	ds_write_b128 v179, v[128:131] offset:27648
	s_waitcnt vmcnt(6)
	ds_write_b128 v217, v[132:135] offset:64512
	global_load_dwordx4 v[128:131], v[224:225], off offset:768
	global_load_dwordx4 v[132:135], v[226:227], off
	s_waitcnt lgkmcnt(0)
	s_barrier
; DI f32x16 mfma32(bf16x8 a, bf16x8 b, f32x16 c) { return __builtin_amdgcn_mfma_f32_32x32x16_bf16(a, b, c, 0, 0, 0); }
; DI s16x4 tr_read(const char* p) { bfx4 r = __builtin_amdgcn_ds_read_tr16_b64_v4bf16((LDS_AS bfx4*)p); return __builtin_bit_cast(s16x4, r); }
; DI bf16x8 cat8(s16x4 lo, s16x4 hi) { return __builtin_shufflevector(lo, hi, 0, 1, 2, 3, 4, 5, 6, 7); }
; template <int BM, class Epi>
; DI void gemm_tile(const bf16_t* __restrict__ A, int lda, const bf16_t* __restrict__ B, int ldb, int K, int row0, int col0, const Epi& epi, char* smem) {
;     ...
;     for (int kt = 0; kt < nk; ++kt) {
;         const char* cur = smem + (kt & 1) * GSTAGE;
;         char* nxt = smem + ((kt & 1) ^ 1) * GSTAGE;
;         const bool w1 = kt + 1 < nk, l2 = kt + 2 < nk;
;         const bf16_t* a2 = ag + (size_t)(kt + 2) * 64; const bf16_t* b2 = bg + (size_t)(kt + 2) * 64 * ldb;
; #pragma unroll
;         for (int s = 0; s < 4; ++s) {
;             bf16x8 xf[MI], wf[2];
; #pragma unroll
;             for (int mi = 0; mi < MI; ++mi) xf[mi] = *(const bf16x8*)(cur + xoff + mi * 32 * GA_S + s * 32);
; #pragma unroll
;             for (int ni = 0; ni < 2; ++ni) {
;                 const char* wp = cur + woff + s * 16 * GB_S + ni * 64;
;                 wf[ni] = cat8(tr_read(wp), tr_read(wp + 4 * GB_S));
;             }
; #pragma unroll
;             for (int mi = 0; mi < MI; ++mi)
; #pragma unroll
;                 for (int ni = 0; ni < 2; ++ni) acc[mi][ni] = mfma32(wf[ni], xf[mi], acc[mi][ni]);
;             if (w1) {
;                 if (s < NA_) *(u32x4*)(nxt + aw + 64 * s * GA_S) = ra[s];
;                 *(u32x4*)(nxt + bw + 16 * s * GB_S) = rb[s];
;             }
;             if (l2) {
;                 if (s < NA_) ra[s] = *(const u32x4*)(a2 + (size_t)(64 * s) * lda);
;                 rb[s] = *(const u32x4*)(b2 + (size_t)(16 * s) * ldb);
;             }
;         }
;         __syncthreads();
;     }
	v_mfma_f32_32x32x16_bf16 v[16:31], v[180:183], v[188:191], v[16:31]
	v_mfma_f32_32x32x16_bf16 v[0:15], v[184:187], v[188:191], v[0:15]
	s_cbranch_scc0 .LBB0_76
	s_add_i32 s0, 0, 0x12000
	v_add3_u32 v167, 0, v165, v174
	v_add3_u32 v166, v177, v162, s0
	v_add3_u32 v172, 0, v175, v176
	ds_read_b128 v[160:163], v167
	ds_read_b128 v[178:181], v167 offset:4608
	ds_read_b128 v[182:185], v167 offset:9216
	ds_read_b128 v[186:189], v167 offset:13824
	ds_read_b64_tr_b16 v[190:191], v172 offset:36864
	ds_read_b64_tr_b16 v[192:193], v172 offset:39168
	ds_read_b64_tr_b16 v[218:219], v172 offset:36928
	ds_read_b64_tr_b16 v[220:221], v172 offset:39232
	s_waitcnt lgkmcnt(2)
	v_mfma_f32_32x32x16_bf16 v[112:127], v[190:193], v[160:163], v[112:127]
	v_add_u32_e32 v164, s0, v164
	s_waitcnt vmcnt(7)
	ds_write_b128 v164, v[152:155]
	s_waitcnt vmcnt(6)
	ds_write_b128 v166, v[156:159] offset:36864
	v_add_u32_e32 v177, 0x9000, v172
	s_add_i32 s2, s2, s13
	s_cmpk_gt_i32 s2, 0x1ff
	s_waitcnt lgkmcnt(2)
	v_mfma_f32_32x32x16_bf16 v[96:111], v[218:221], v[160:163], v[96:111]
	v_mfma_f32_32x32x16_bf16 v[48:63], v[190:193], v[182:185], v[48:63]
	v_mfma_f32_32x32x16_bf16 v[32:47], v[218:221], v[182:185], v[32:47]
	v_mfma_f32_32x32x16_bf16 v[80:95], v[190:193], v[178:181], v[80:95]
	v_mfma_f32_32x32x16_bf16 v[64:79], v[218:221], v[178:181], v[64:79]
	v_mfma_f32_32x32x16_bf16 v[16:31], v[190:193], v[186:189], v[16:31]
	v_mfma_f32_32x32x16_bf16 v[0:15], v[218:221], v[186:189], v[0:15]
	ds_read_b128 v[152:155], v167 offset:32
	ds_read_b128 v[156:159], v167 offset:4640
	ds_read_b128 v[160:163], v167 offset:9248
	ds_read_b128 v[178:181], v167 offset:13856
	ds_read_b64_tr_b16 v[182:183], v172 offset:46080
	ds_read_b64_tr_b16 v[184:185], v172 offset:48384
	ds_read_b64_tr_b16 v[186:187], v172 offset:46144
	ds_read_b64_tr_b16 v[188:189], v172 offset:48448
	s_waitcnt vmcnt(5)
	ds_write_b128 v164, v[144:147] offset:9216
	s_waitcnt vmcnt(4)
	ds_write_b128 v166, v[148:151] offset:46080
	s_waitcnt lgkmcnt(4)
	v_mfma_f32_32x32x16_bf16 v[112:127], v[182:185], v[152:155], v[112:127]
	s_waitcnt lgkmcnt(2)
	v_mfma_f32_32x32x16_bf16 v[96:111], v[186:189], v[152:155], v[96:111]
	v_mfma_f32_32x32x16_bf16 v[48:63], v[182:185], v[160:163], v[48:63]
	v_mfma_f32_32x32x16_bf16 v[32:47], v[186:189], v[160:163], v[32:47]
	v_mfma_f32_32x32x16_bf16 v[80:95], v[182:185], v[156:159], v[80:95]
	v_mfma_f32_32x32x16_bf16 v[64:79], v[186:189], v[156:159], v[64:79]
	v_mfma_f32_32x32x16_bf16 v[16:31], v[182:185], v[178:181], v[16:31]
	v_mfma_f32_32x32x16_bf16 v[0:15], v[186:189], v[178:181], v[0:15]
	ds_read_b128 v[144:147], v167 offset:64
	ds_read_b128 v[148:151], v167 offset:4672
	ds_read_b128 v[152:155], v167 offset:9280
	ds_read_b128 v[156:159], v167 offset:13888
	ds_read_b64_tr_b16 v[160:161], v172 offset:55296
	ds_read_b64_tr_b16 v[162:163], v172 offset:57600
	ds_read_b64_tr_b16 v[178:179], v172 offset:55360
	ds_read_b64_tr_b16 v[180:181], v172 offset:57664
	s_waitcnt vmcnt(3)
	ds_write_b128 v164, v[136:139] offset:18432
	s_waitcnt vmcnt(2)
	ds_write_b128 v166, v[140:143] offset:55296
	s_waitcnt lgkmcnt(4)
	v_mfma_f32_32x32x16_bf16 v[112:127], v[160:163], v[144:147], v[112:127]
	s_waitcnt lgkmcnt(2)
	v_mfma_f32_32x32x16_bf16 v[96:111], v[178:181], v[144:147], v[96:111]
	v_mfma_f32_32x32x16_bf16 v[48:63], v[160:163], v[152:155], v[48:63]
	v_mfma_f32_32x32x16_bf16 v[32:47], v[178:181], v[152:155], v[32:47]
	v_mfma_f32_32x32x16_bf16 v[80:95], v[160:163], v[148:151], v[80:95]
	v_mfma_f32_32x32x16_bf16 v[64:79], v[178:181], v[148:151], v[64:79]
	v_mfma_f32_32x32x16_bf16 v[16:31], v[160:163], v[156:159], v[16:31]
	v_mfma_f32_32x32x16_bf16 v[0:15], v[178:181], v[156:159], v[0:15]
	ds_read_b128 v[136:139], v167 offset:96
	ds_read_b128 v[140:143], v167 offset:4704
	ds_read_b128 v[144:147], v167 offset:9312
	ds_read_b128 v[148:151], v167 offset:13920
	ds_read_b64_tr_b16 v[152:153], v172 offset:64512
	ds_read_b64_tr_b16 v[154:155], v177 offset:29952
	ds_read_b64_tr_b16 v[156:157], v172 offset:64576
	ds_read_b64_tr_b16 v[158:159], v177 offset:30016
	s_waitcnt vmcnt(1)
	ds_write_b128 v164, v[128:131] offset:27648
	s_waitcnt vmcnt(0)
	ds_write_b128 v166, v[132:135] offset:64512
	s_waitcnt lgkmcnt(0)
	s_barrier
	v_mfma_f32_32x32x16_bf16 v[112:127], v[152:155], v[136:139], v[112:127]
	v_mfma_f32_32x32x16_bf16 v[96:111], v[156:159], v[136:139], v[96:111]
	v_mfma_f32_32x32x16_bf16 v[48:63], v[152:155], v[144:147], v[48:63]
	v_mfma_f32_32x32x16_bf16 v[32:47], v[156:159], v[144:147], v[32:47]
	v_mfma_f32_32x32x16_bf16 v[80:95], v[152:155], v[140:143], v[80:95]
	v_mfma_f32_32x32x16_bf16 v[64:79], v[156:159], v[140:143], v[64:79]
	v_mfma_f32_32x32x16_bf16 v[16:31], v[152:155], v[148:151], v[16:31]
	v_mfma_f32_32x32x16_bf16 v[0:15], v[156:159], v[148:151], v[0:15]
	v_add3_u32 v156, s0, v165, v174
	v_add3_u32 v157, s0, v175, v176
	ds_read_b128 v[128:131], v156 offset:4608
	ds_read_b128 v[132:135], v156 offset:9216
	ds_read_b128 v[136:139], v156 offset:13824
	ds_read_b64_tr_b16 v[140:141], v157 offset:36864
	ds_read_b64_tr_b16 v[142:143], v157 offset:39168
	ds_read_b64_tr_b16 v[144:145], v157 offset:36928
	ds_read_b64_tr_b16 v[146:147], v157 offset:39232
	ds_read_b128 v[148:151], v156
	ds_read_b128 v[152:155], v156 offset:32
	v_add_u32_e32 v158, 0x9000, v157
	v_readlane_b32 s0, v253, 3
	v_readlane_b32 s1, v253, 4
	s_waitcnt lgkmcnt(1)
; DI unsigned pk2(float a, float b) { f32x2 v = {a, b}; bfx2 r = __builtin_convertvector(v, bfx2); return __builtin_bit_cast(unsigned, r); }
; DI f32x16 mfma32(bf16x8 a, bf16x8 b, f32x16 c) { return __builtin_amdgcn_mfma_f32_32x32x16_bf16(a, b, c, 0, 0, 0); }
; DI s16x4 tr_read(const char* p) { bfx4 r = __builtin_amdgcn_ds_read_tr16_b64_v4bf16((LDS_AS bfx4*)p); return __builtin_bit_cast(s16x4, r); }
; template <int BM, class Epi>
; DI void gemm_tile(const bf16_t* __restrict__ A, int lda, const bf16_t* __restrict__ B, int ldb, int K, int row0, int col0, const Epi& epi, char* smem) {
;     ...
;         for (int s = 0; s < 4; ++s) {
;             bf16x8 xf[MI], wf[2];
; #pragma unroll
;             for (int mi = 0; mi < MI; ++mi) xf[mi] = *(const bf16x8*)(cur + xoff + mi * 32 * GA_S + s * 32);
; #pragma unroll
;             for (int ni = 0; ni < 2; ++ni) {
;                 const char* wp = cur + woff + s * 16 * GB_S + ni * 64;
;                 wf[ni] = cat8(tr_read(wp), tr_read(wp + 4 * GB_S));
;             }
; #pragma unroll
;             for (int mi = 0; mi < MI; ++mi)
; #pragma unroll
;                 for (int ni = 0; ni < 2; ++ni) acc[mi][ni] = mfma32(wf[ni], xf[mi], acc[mi][ni]);
;             if (w1) {
;                 if (s < NA_) *(u32x4*)(nxt + aw + 64 * s * GA_S) = ra[s];
;                 *(u32x4*)(nxt + bw + 16 * s * GB_S) = rb[s];
;             }
;             if (l2) {
;                 if (s < NA_) ra[s] = *(const u32x4*)(a2 + (size_t)(64 * s) * lda);
;                 rb[s] = *(const u32x4*)(b2 + (size_t)(16 * s) * ldb);
;             }
;         }
;         __syncthreads();
;     DI void operator()(const f32x16& a0, const f32x16& a1, int row, int cbase, int hh) const {
;         const int s = row < RL ? (row >> 13) : 4;
;         const float* gp = gate + s * 9216;
;         bf16_t* yp = Y + (size_t)row * 1024;
; #pragma unroll
;         for (int ni = 0; ni < 2; ++ni)
; #pragma unroll
;             for (int q4 = 0; q4 < 4; ++q4) {
;                 const int c = cbase + ni * 32 + 8 * q4 + 4 * hh;
;                 const f32x4 g = *(const f32x4*)(gp + c);
;                 const f32x16& v = ni ? a1 : a0;
;                 u32x2 w; w.x = pk2(coef * g[0] * v[4 * q4], coef * g[1] * v[4 * q4 + 1]); w.y = pk2(coef * g[2] * v[4 * q4 + 2], coef * g[3] * v[4 * q4 + 3]);
;                 *(u32x2*)(yp + c) = w;
;             }
	v_mfma_f32_32x32x16_bf16 v[112:127], v[140:143], v[148:151], v[112:127]
	v_mfma_f32_32x32x16_bf16 v[96:111], v[144:147], v[148:151], v[96:111]
	v_mfma_f32_32x32x16_bf16 v[48:63], v[140:143], v[132:135], v[48:63]
	v_mfma_f32_32x32x16_bf16 v[32:47], v[144:147], v[132:135], v[32:47]
	v_mfma_f32_32x32x16_bf16 v[80:95], v[140:143], v[128:131], v[80:95]
	v_mfma_f32_32x32x16_bf16 v[64:79], v[144:147], v[128:131], v[64:79]
	v_mfma_f32_32x32x16_bf16 v[16:31], v[140:143], v[136:139], v[16:31]
	v_mfma_f32_32x32x16_bf16 v[0:15], v[144:147], v[136:139], v[0:15]
	ds_read_b128 v[128:131], v156 offset:4640
	ds_read_b128 v[132:135], v156 offset:9248
	ds_read_b128 v[136:139], v156 offset:13856
	ds_read_b64_tr_b16 v[140:141], v157 offset:46080
	ds_read_b64_tr_b16 v[142:143], v157 offset:48384
	ds_read_b64_tr_b16 v[144:145], v157 offset:46144
	ds_read_b64_tr_b16 v[146:147], v157 offset:48448
	s_waitcnt lgkmcnt(2)
	v_mfma_f32_32x32x16_bf16 v[112:127], v[140:143], v[152:155], v[112:127]
	s_waitcnt lgkmcnt(0)
	v_mfma_f32_32x32x16_bf16 v[96:111], v[144:147], v[152:155], v[96:111]
	v_mfma_f32_32x32x16_bf16 v[48:63], v[140:143], v[132:135], v[48:63]
	v_mfma_f32_32x32x16_bf16 v[32:47], v[144:147], v[132:135], v[32:47]
	v_mfma_f32_32x32x16_bf16 v[80:95], v[140:143], v[128:131], v[80:95]
	v_mfma_f32_32x32x16_bf16 v[64:79], v[144:147], v[128:131], v[64:79]
	v_mfma_f32_32x32x16_bf16 v[16:31], v[140:143], v[136:139], v[16:31]
	v_mfma_f32_32x32x16_bf16 v[0:15], v[144:147], v[136:139], v[0:15]
	ds_read_b128 v[128:131], v156 offset:64
	ds_read_b128 v[132:135], v156 offset:4672
	ds_read_b128 v[136:139], v156 offset:9280
	ds_read_b128 v[140:143], v156 offset:13888
	ds_read_b64_tr_b16 v[144:145], v157 offset:55296
	ds_read_b64_tr_b16 v[146:147], v157 offset:57600
	ds_read_b64_tr_b16 v[148:149], v157 offset:55360
	ds_read_b64_tr_b16 v[150:151], v157 offset:57664
	s_waitcnt lgkmcnt(2)
	v_mfma_f32_32x32x16_bf16 v[112:127], v[144:147], v[128:131], v[112:127]
	s_waitcnt lgkmcnt(0)
	v_mfma_f32_32x32x16_bf16 v[96:111], v[148:151], v[128:131], v[96:111]
	v_mfma_f32_32x32x16_bf16 v[48:63], v[144:147], v[136:139], v[48:63]
	v_mfma_f32_32x32x16_bf16 v[32:47], v[148:151], v[136:139], v[32:47]
	v_mfma_f32_32x32x16_bf16 v[80:95], v[144:147], v[132:135], v[80:95]
	v_mfma_f32_32x32x16_bf16 v[64:79], v[148:151], v[132:135], v[64:79]
	v_mfma_f32_32x32x16_bf16 v[16:31], v[144:147], v[140:143], v[16:31]
	v_mfma_f32_32x32x16_bf16 v[0:15], v[148:151], v[140:143], v[0:15]
	ds_read_b128 v[128:131], v156 offset:96
	ds_read_b128 v[132:135], v156 offset:4704
	ds_read_b128 v[136:139], v156 offset:9312
	ds_read_b128 v[140:143], v156 offset:13920
	ds_read_b64_tr_b16 v[144:145], v157 offset:64512
	ds_read_b64_tr_b16 v[146:147], v158 offset:29952
	ds_read_b64_tr_b16 v[148:149], v157 offset:64576
	ds_read_b64_tr_b16 v[150:151], v158 offset:30016
	s_waitcnt lgkmcnt(0)
	s_barrier
	v_mfma_f32_32x32x16_bf16 v[112:127], v[144:147], v[128:131], v[112:127]
	v_mfma_f32_32x32x16_bf16 v[96:111], v[148:151], v[128:131], v[96:111]
	v_or_b32_e32 v128, s3, v169
	v_and_b32_e32 v129, 0xc0, v168
	v_add_u32_e32 v128, v128, v171
	v_lshlrev_b32_e32 v130, 2, v170
	v_mfma_f32_32x32x16_bf16 v[48:63], v[144:147], v[136:139], v[48:63]
	v_mfma_f32_32x32x16_bf16 v[32:47], v[148:151], v[136:139], v[32:47]
	v_or3_b32 v136, v130, v129, s10
	v_min_i32_e32 v129, 0x8000, v128
	v_ashrrev_i32_e32 v129, 13, v129
	v_mul_i32_i24_e32 v130, 0x2400, v129
	v_ashrrev_i32_e32 v131, 31, v130
	v_ashrrev_i32_e32 v129, 31, v128
	v_ashrrev_i32_e32 v137, 31, v136
	v_mfma_f32_32x32x16_bf16 v[80:95], v[144:147], v[132:135], v[80:95]
	v_mfma_f32_32x32x16_bf16 v[64:79], v[148:151], v[132:135], v[64:79]
	v_lshl_add_u64 v[132:133], v[130:131], 2, s[4:5]
	v_lshlrev_b64 v[130:131], 11, v[128:129]
	v_lshl_add_u64 v[138:139], s[0:1], 0, v[130:131]
	v_lshlrev_b64 v[130:131], 2, v[136:137]
	v_mfma_f32_32x32x16_bf16 v[16:31], v[144:147], v[140:143], v[16:31]
	v_mfma_f32_32x32x16_bf16 v[0:15], v[148:151], v[140:143], v[0:15]
	v_lshl_add_u64 v[140:141], v[132:133], 0, v[130:131]
	global_load_dwordx4 v[228:231], v[140:141], off
	global_load_dwordx4 v[232:235], v[140:141], off offset:32
	global_load_dwordx4 v[236:239], v[140:141], off offset:64
	global_load_dwordx4 v[240:243], v[140:141], off offset:96
	s_waitcnt vmcnt(0)
	v_mul_f32_e64 v112, v112, v228
	v_mul_f32_e64 v113, v113, v229
	v_cvt_pk_bf16_f32 v132, v112, v113
	v_pk_mul_f32 v[112:113], v[114:115], v[230:231]
	s_nop 0
	v_cvt_pk_bf16_f32 v133, v112, v113
	v_lshlrev_b64 v[112:113], 1, v[136:137]
	v_lshl_add_u64 v[136:137], v[138:139], 0, v[112:113]
	global_store_dwordx2 v[136:137], v[132:133], off
	v_pk_mul_f32 v[114:115], v[116:117], v[232:233]
	v_pk_mul_f32 v[116:117], v[118:119], v[234:235]
	v_cvt_pk_bf16_f32 v114, v114, v115
	v_cvt_pk_bf16_f32 v115, v116, v117
	global_store_dwordx2 v[136:137], v[114:115], off offset:16
	v_pk_mul_f32 v[114:115], v[120:121], v[236:237]
	v_pk_mul_f32 v[116:117], v[122:123], v[238:239]
	v_cvt_pk_bf16_f32 v114, v114, v115
	v_cvt_pk_bf16_f32 v115, v116, v117
	global_store_dwordx2 v[136:137], v[114:115], off offset:32
	v_pk_mul_f32 v[114:115], v[124:125], v[240:241]
	v_pk_mul_f32 v[116:117], v[126:127], v[242:243]
	v_cvt_pk_bf16_f32 v114, v114, v115
	v_cvt_pk_bf16_f32 v115, v116, v117
	global_store_dwordx2 v[136:137], v[114:115], off offset:48
	global_load_dwordx4 v[228:231], v[140:141], off offset:128
	global_load_dwordx4 v[232:235], v[140:141], off offset:160
	global_load_dwordx4 v[236:239], v[140:141], off offset:192
	global_load_dwordx4 v[240:243], v[140:141], off offset:224
	s_waitcnt vmcnt(0)
; DI unsigned pk2(float a, float b) { f32x2 v = {a, b}; bfx2 r = __builtin_convertvector(v, bfx2); return __builtin_bit_cast(unsigned, r); }
;     DI void operator()(const f32x16& a0, const f32x16& a1, int row, int cbase, int hh) const {
;         const int s = row < RL ? (row >> 13) : 4;
;         const float* gp = gate + s * 9216;
;         bf16_t* yp = Y + (size_t)row * 1024;
; #pragma unroll
;         for (int ni = 0; ni < 2; ++ni)
; #pragma unroll
;             for (int q4 = 0; q4 < 4; ++q4) {
;                 const int c = cbase + ni * 32 + 8 * q4 + 4 * hh;
;                 const f32x4 g = *(const f32x4*)(gp + c);
;                 const f32x16& v = ni ? a1 : a0;
;                 u32x2 w; w.x = pk2(coef * g[0] * v[4 * q4], coef * g[1] * v[4 * q4 + 1]); w.y = pk2(coef * g[2] * v[4 * q4 + 2], coef * g[3] * v[4 * q4 + 3]);
;                 *(u32x2*)(yp + c) = w;
;             }
	v_pk_mul_f32 v[96:97], v[96:97], v[228:229]
	v_pk_mul_f32 v[98:99], v[98:99], v[230:231]
	v_cvt_pk_bf16_f32 v96, v96, v97
	v_cvt_pk_bf16_f32 v97, v98, v99
	global_store_dwordx2 v[136:137], v[96:97], off offset:64
	v_pk_mul_f32 v[96:97], v[100:101], v[232:233]
	v_pk_mul_f32 v[98:99], v[102:103], v[234:235]
	v_cvt_pk_bf16_f32 v96, v96, v97
	v_cvt_pk_bf16_f32 v97, v98, v99
	global_store_dwordx2 v[136:137], v[96:97], off offset:80
	v_pk_mul_f32 v[96:97], v[104:105], v[236:237]
	v_pk_mul_f32 v[98:99], v[106:107], v[238:239]
	v_cvt_pk_bf16_f32 v96, v96, v97
	v_cvt_pk_bf16_f32 v97, v98, v99
	global_store_dwordx2 v[136:137], v[96:97], off offset:96
	v_pk_mul_f32 v[96:97], v[108:109], v[240:241]
	v_pk_mul_f32 v[98:99], v[110:111], v[242:243]
	v_cvt_pk_bf16_f32 v96, v96, v97
	v_cvt_pk_bf16_f32 v97, v98, v99
	global_store_dwordx2 v[136:137], v[96:97], off offset:112
	v_or_b32_e32 v96, 32, v128
	v_min_i32_e32 v97, 0x8000, v96
	v_ashrrev_i32_e32 v97, 13, v97
	v_mul_i32_i24_e32 v98, 0x2400, v97
	v_ashrrev_i32_e32 v99, 31, v98
	v_lshl_add_u64 v[98:99], v[98:99], 2, s[4:5]
	v_ashrrev_i32_e32 v97, 31, v96
	v_lshlrev_b64 v[96:97], 11, v[96:97]
	v_lshl_add_u64 v[102:103], v[98:99], 0, v[130:131]
	v_lshl_add_u64 v[100:101], s[0:1], 0, v[96:97]
	global_load_dwordx4 v[228:231], v[102:103], off
	global_load_dwordx4 v[232:235], v[102:103], off offset:32
	global_load_dwordx4 v[236:239], v[102:103], off offset:64
	global_load_dwordx4 v[240:243], v[102:103], off offset:96
	s_waitcnt vmcnt(0)
	v_pk_mul_f32 v[80:81], v[80:81], v[228:229]
	v_pk_mul_f32 v[82:83], v[82:83], v[230:231]
	v_cvt_pk_bf16_f32 v80, v80, v81
	v_cvt_pk_bf16_f32 v81, v82, v83
	v_lshl_add_u64 v[96:97], v[100:101], 0, v[112:113]
	global_store_dwordx2 v[96:97], v[80:81], off
	v_pk_mul_f32 v[80:81], v[84:85], v[232:233]
	v_pk_mul_f32 v[82:83], v[86:87], v[234:235]
	v_cvt_pk_bf16_f32 v80, v80, v81
	v_cvt_pk_bf16_f32 v81, v82, v83
	global_store_dwordx2 v[96:97], v[80:81], off offset:16
	v_pk_mul_f32 v[80:81], v[88:89], v[236:237]
	v_pk_mul_f32 v[82:83], v[90:91], v[238:239]
	v_cvt_pk_bf16_f32 v80, v80, v81
	v_cvt_pk_bf16_f32 v81, v82, v83
	global_store_dwordx2 v[96:97], v[80:81], off offset:32
	v_pk_mul_f32 v[80:81], v[92:93], v[240:241]
	v_pk_mul_f32 v[82:83], v[94:95], v[242:243]
	v_cvt_pk_bf16_f32 v80, v80, v81
	v_cvt_pk_bf16_f32 v81, v82, v83
	global_store_dwordx2 v[96:97], v[80:81], off offset:48
	global_load_dwordx4 v[228:231], v[102:103], off offset:128
	global_load_dwordx4 v[232:235], v[102:103], off offset:160
	global_load_dwordx4 v[236:239], v[102:103], off offset:192
	global_load_dwordx4 v[240:243], v[102:103], off offset:224
	s_waitcnt vmcnt(0)
	v_pk_mul_f32 v[64:65], v[64:65], v[228:229]
	v_pk_mul_f32 v[66:67], v[66:67], v[230:231]
	v_cvt_pk_bf16_f32 v64, v64, v65
	v_cvt_pk_bf16_f32 v65, v66, v67
	global_store_dwordx2 v[96:97], v[64:65], off offset:64
	v_pk_mul_f32 v[64:65], v[68:69], v[232:233]
	v_pk_mul_f32 v[66:67], v[70:71], v[234:235]
	v_cvt_pk_bf16_f32 v64, v64, v65
	v_cvt_pk_bf16_f32 v65, v66, v67
	global_store_dwordx2 v[96:97], v[64:65], off offset:80
	v_pk_mul_f32 v[64:65], v[72:73], v[236:237]
	v_pk_mul_f32 v[66:67], v[74:75], v[238:239]
	v_cvt_pk_bf16_f32 v64, v64, v65
	v_cvt_pk_bf16_f32 v65, v66, v67
	global_store_dwordx2 v[96:97], v[64:65], off offset:96
	v_pk_mul_f32 v[64:65], v[76:77], v[240:241]
	v_pk_mul_f32 v[66:67], v[78:79], v[242:243]
	v_cvt_pk_bf16_f32 v64, v64, v65
	v_cvt_pk_bf16_f32 v65, v66, v67
	global_store_dwordx2 v[96:97], v[64:65], off offset:112
	v_or_b32_e32 v64, 64, v128
	v_min_i32_e32 v65, 0x8000, v64
	v_ashrrev_i32_e32 v65, 13, v65
	v_mul_i32_i24_e32 v66, 0x2400, v65
	v_ashrrev_i32_e32 v67, 31, v66
	v_lshl_add_u64 v[66:67], v[66:67], 2, s[4:5]
	v_ashrrev_i32_e32 v65, 31, v64
	v_lshlrev_b64 v[64:65], 11, v[64:65]
	v_lshl_add_u64 v[70:71], v[66:67], 0, v[130:131]
	v_lshl_add_u64 v[68:69], s[0:1], 0, v[64:65]
	global_load_dwordx4 v[228:231], v[70:71], off
	global_load_dwordx4 v[232:235], v[70:71], off offset:32
	global_load_dwordx4 v[236:239], v[70:71], off offset:64
	global_load_dwordx4 v[240:243], v[70:71], off offset:96
	s_waitcnt vmcnt(0)
; DI unsigned pk2(float a, float b) { f32x2 v = {a, b}; bfx2 r = __builtin_convertvector(v, bfx2); return __builtin_bit_cast(unsigned, r); }
;     DI void operator()(const f32x16& a0, const f32x16& a1, int row, int cbase, int hh) const {
;         const int s = row < RL ? (row >> 13) : 4;
;         const float* gp = gate + s * 9216;
;         bf16_t* yp = Y + (size_t)row * 1024;
; #pragma unroll
;         for (int ni = 0; ni < 2; ++ni)
; #pragma unroll
;             for (int q4 = 0; q4 < 4; ++q4) {
;                 const int c = cbase + ni * 32 + 8 * q4 + 4 * hh;
;                 const f32x4 g = *(const f32x4*)(gp + c);
;                 const f32x16& v = ni ? a1 : a0;
;                 u32x2 w; w.x = pk2(coef * g[0] * v[4 * q4], coef * g[1] * v[4 * q4 + 1]); w.y = pk2(coef * g[2] * v[4 * q4 + 2], coef * g[3] * v[4 * q4 + 3]);
;                 *(u32x2*)(yp + c) = w;
;             }
	v_pk_mul_f32 v[48:49], v[48:49], v[228:229]
	v_pk_mul_f32 v[50:51], v[50:51], v[230:231]
	v_cvt_pk_bf16_f32 v48, v48, v49
	v_cvt_pk_bf16_f32 v49, v50, v51
	v_lshl_add_u64 v[64:65], v[68:69], 0, v[112:113]
	global_store_dwordx2 v[64:65], v[48:49], off
	v_pk_mul_f32 v[48:49], v[52:53], v[232:233]
	v_pk_mul_f32 v[50:51], v[54:55], v[234:235]
	v_cvt_pk_bf16_f32 v48, v48, v49
	v_cvt_pk_bf16_f32 v49, v50, v51
	global_store_dwordx2 v[64:65], v[48:49], off offset:16
	v_pk_mul_f32 v[48:49], v[56:57], v[236:237]
	v_pk_mul_f32 v[50:51], v[58:59], v[238:239]
	v_cvt_pk_bf16_f32 v48, v48, v49
	v_cvt_pk_bf16_f32 v49, v50, v51
	global_store_dwordx2 v[64:65], v[48:49], off offset:32
	v_pk_mul_f32 v[48:49], v[60:61], v[240:241]
	v_pk_mul_f32 v[50:51], v[62:63], v[242:243]
	v_cvt_pk_bf16_f32 v48, v48, v49
	v_cvt_pk_bf16_f32 v49, v50, v51
	global_store_dwordx2 v[64:65], v[48:49], off offset:48
	global_load_dwordx4 v[228:231], v[70:71], off offset:128
	global_load_dwordx4 v[232:235], v[70:71], off offset:160
	global_load_dwordx4 v[236:239], v[70:71], off offset:192
	global_load_dwordx4 v[240:243], v[70:71], off offset:224
	s_waitcnt vmcnt(0)
	v_pk_mul_f32 v[32:33], v[32:33], v[228:229]
	v_pk_mul_f32 v[34:35], v[34:35], v[230:231]
	v_cvt_pk_bf16_f32 v32, v32, v33
	v_cvt_pk_bf16_f32 v33, v34, v35
	global_store_dwordx2 v[64:65], v[32:33], off offset:64
	v_pk_mul_f32 v[32:33], v[36:37], v[232:233]
	v_pk_mul_f32 v[34:35], v[38:39], v[234:235]
	v_cvt_pk_bf16_f32 v32, v32, v33
	v_cvt_pk_bf16_f32 v33, v34, v35
	global_store_dwordx2 v[64:65], v[32:33], off offset:80
	v_pk_mul_f32 v[32:33], v[40:41], v[236:237]
	v_pk_mul_f32 v[34:35], v[42:43], v[238:239]
	v_cvt_pk_bf16_f32 v32, v32, v33
	v_cvt_pk_bf16_f32 v33, v34, v35
	global_store_dwordx2 v[64:65], v[32:33], off offset:96
	v_pk_mul_f32 v[32:33], v[44:45], v[240:241]
	v_pk_mul_f32 v[34:35], v[46:47], v[242:243]
	v_cvt_pk_bf16_f32 v32, v32, v33
	v_cvt_pk_bf16_f32 v33, v34, v35
	global_store_dwordx2 v[64:65], v[32:33], off offset:112
	v_or_b32_e32 v32, 0x60, v128
	v_min_i32_e32 v33, 0x8000, v32
	v_ashrrev_i32_e32 v33, 13, v33
	v_mul_i32_i24_e32 v34, 0x2400, v33
	v_ashrrev_i32_e32 v35, 31, v34
	v_lshl_add_u64 v[34:35], v[34:35], 2, s[4:5]
	v_ashrrev_i32_e32 v33, 31, v32
	v_lshlrev_b64 v[32:33], 11, v[32:33]
	v_lshl_add_u64 v[38:39], v[34:35], 0, v[130:131]
	v_lshl_add_u64 v[36:37], s[0:1], 0, v[32:33]
	global_load_dwordx4 v[228:231], v[38:39], off
	global_load_dwordx4 v[232:235], v[38:39], off offset:32
	global_load_dwordx4 v[236:239], v[38:39], off offset:64
	global_load_dwordx4 v[240:243], v[38:39], off offset:96
	s_waitcnt vmcnt(0)
	v_pk_mul_f32 v[16:17], v[16:17], v[228:229]
	v_pk_mul_f32 v[18:19], v[18:19], v[230:231]
	v_cvt_pk_bf16_f32 v16, v16, v17
	v_cvt_pk_bf16_f32 v17, v18, v19
	v_lshl_add_u64 v[32:33], v[36:37], 0, v[112:113]
	global_store_dwordx2 v[32:33], v[16:17], off
	v_pk_mul_f32 v[16:17], v[20:21], v[232:233]
	v_pk_mul_f32 v[18:19], v[22:23], v[234:235]
	v_cvt_pk_bf16_f32 v16, v16, v17
	v_cvt_pk_bf16_f32 v17, v18, v19
	global_store_dwordx2 v[32:33], v[16:17], off offset:16
	v_pk_mul_f32 v[16:17], v[24:25], v[236:237]
	v_pk_mul_f32 v[18:19], v[26:27], v[238:239]
	v_cvt_pk_bf16_f32 v16, v16, v17
	v_cvt_pk_bf16_f32 v17, v18, v19
	global_store_dwordx2 v[32:33], v[16:17], off offset:32
	v_pk_mul_f32 v[16:17], v[28:29], v[240:241]
	v_pk_mul_f32 v[18:19], v[30:31], v[242:243]
	v_cvt_pk_bf16_f32 v16, v16, v17
	v_cvt_pk_bf16_f32 v17, v18, v19
	global_store_dwordx2 v[32:33], v[16:17], off offset:48
	global_load_dwordx4 v[228:231], v[38:39], off offset:128
	global_load_dwordx4 v[232:235], v[38:39], off offset:160
	global_load_dwordx4 v[236:239], v[38:39], off offset:192
	global_load_dwordx4 v[240:243], v[38:39], off offset:224
	s_waitcnt vmcnt(0)
	v_pk_mul_f32 v[0:1], v[0:1], v[228:229]
	v_pk_mul_f32 v[2:3], v[2:3], v[230:231]
	v_cvt_pk_bf16_f32 v0, v0, v1
	v_cvt_pk_bf16_f32 v1, v2, v3
	global_store_dwordx2 v[32:33], v[0:1], off offset:64
	v_pk_mul_f32 v[0:1], v[4:5], v[232:233]
	v_pk_mul_f32 v[2:3], v[6:7], v[234:235]
	v_cvt_pk_bf16_f32 v0, v0, v1
	v_cvt_pk_bf16_f32 v1, v2, v3
	global_store_dwordx2 v[32:33], v[0:1], off offset:80
	v_pk_mul_f32 v[0:1], v[8:9], v[236:237]
	v_pk_mul_f32 v[2:3], v[10:11], v[238:239]
	v_cvt_pk_bf16_f32 v0, v0, v1
	v_cvt_pk_bf16_f32 v1, v2, v3
	global_store_dwordx2 v[32:33], v[0:1], off offset:96
	v_pk_mul_f32 v[0:1], v[12:13], v[240:241]
	v_pk_mul_f32 v[2:3], v[14:15], v[242:243]
	v_cvt_pk_bf16_f32 v0, v0, v1
	v_cvt_pk_bf16_f32 v1, v2, v3
	global_store_dwordx2 v[32:33], v[0:1], off offset:112
	s_cbranch_scc0 .LBB0_75

; DI f32x16 mfma32(bf16x8 a, bf16x8 b, f32x16 c) { return __builtin_amdgcn_mfma_f32_32x32x16_bf16(a, b, c, 0, 0, 0); }
; DI s16x4 tr_read(const char* p) { bfx4 r = __builtin_amdgcn_ds_read_tr16_b64_v4bf16((LDS_AS bfx4*)p); return __builtin_bit_cast(s16x4, r); }
; DI bf16x8 cat8(s16x4 lo, s16x4 hi) { return __builtin_shufflevector(lo, hi, 0, 1, 2, 3, 4, 5, 6, 7); }
; template <int BM, class Epi>
; DI void gemm_tile(const bf16_t* __restrict__ A, int lda, const bf16_t* __restrict__ B, int ldb, int K, int row0, int col0, const Epi& epi, char* smem) {
;     ...
;     for (int kt = 0; kt < nk; ++kt) {
;         const char* cur = smem + (kt & 1) * GSTAGE;
;         char* nxt = smem + ((kt & 1) ^ 1) * GSTAGE;
;         const bool w1 = kt + 1 < nk, l2 = kt + 2 < nk;
;         const bf16_t* a2 = ag + (size_t)(kt + 2) * 64; const bf16_t* b2 = bg + (size_t)(kt + 2) * 64 * ldb;
; #pragma unroll
;         for (int s = 0; s < 4; ++s) {
;             bf16x8 xf[MI], wf[2];
; #pragma unroll
;             for (int mi = 0; mi < MI; ++mi) xf[mi] = *(const bf16x8*)(cur + xoff + mi * 32 * GA_S + s * 32);
; #pragma unroll
;             for (int ni = 0; ni < 2; ++ni) {
;                 const char* wp = cur + woff + s * 16 * GB_S + ni * 64;
;                 wf[ni] = cat8(tr_read(wp), tr_read(wp + 4 * GB_S));
;             }
; #pragma unroll
;             for (int mi = 0; mi < MI; ++mi)
; #pragma unroll
;                 for (int ni = 0; ni < 2; ++ni) acc[mi][ni] = mfma32(wf[ni], xf[mi], acc[mi][ni]);
;             if (w1) {
;                 if (s < NA_) *(u32x4*)(nxt + aw + 64 * s * GA_S) = ra[s];
;                 *(u32x4*)(nxt + bw + 16 * s * GB_S) = rb[s];
;             }
;             if (l2) {
;                 if (s < NA_) ra[s] = *(const u32x4*)(a2 + (size_t)(64 * s) * lda);
;                 rb[s] = *(const u32x4*)(b2 + (size_t)(16 * s) * ldb);
;             }
;         }
;         __syncthreads();
;     }
.LBB0_87:
	s_and_b32 s0, s11, 1
	s_mul_i32 s1, s0, 0x12000
	s_add_i32 s1, s1, 0
	v_add3_u32 v172, s1, v175, v176
	v_add3_u32 v163, s1, v165, v174
	ds_read_b64_tr_b16 v[180:181], v172 offset:36864
	ds_read_b64_tr_b16 v[182:183], v172 offset:39168
	ds_read_b128 v[184:187], v163
	ds_read_b128 v[188:191], v163 offset:4608
	ds_read_b64_tr_b16 v[220:221], v172 offset:39232
	ds_read_b64_tr_b16 v[218:219], v172 offset:36928
	s_xor_b32 s0, s0, 1
	s_mul_i32 s0, s0, 0x12000
	s_add_i32 s0, s0, 0
	v_add_u32_e32 v179, s0, v164
	s_waitcnt lgkmcnt(3)
	v_mfma_f32_32x32x16_bf16 v[112:127], v[180:183], v[184:187], v[112:127]
	v_add_u32_e32 v217, s0, v178
	s_add_i32 s11, s11, 1
	s_cmp_eq_u32 s11, 14
	s_waitcnt lgkmcnt(0)
	v_mfma_f32_32x32x16_bf16 v[96:111], v[218:221], v[184:187], v[96:111]
	v_mfma_f32_32x32x16_bf16 v[80:95], v[180:183], v[188:191], v[80:95]
	v_mfma_f32_32x32x16_bf16 v[64:79], v[218:221], v[188:191], v[64:79]
	ds_read_b128 v[184:187], v163 offset:9216
	ds_read_b128 v[188:191], v163 offset:13824
	s_waitcnt vmcnt(7)
	ds_write_b128 v179, v[152:155]
	s_waitcnt vmcnt(3)
	ds_write_b128 v217, v[156:159] offset:36864
	ds_read_b64_tr_b16 v[152:153], v172 offset:46080
	s_waitcnt lgkmcnt(4)
	v_mfma_f32_32x32x16_bf16 v[48:63], v[180:183], v[184:187], v[48:63]
	v_mfma_f32_32x32x16_bf16 v[32:47], v[218:221], v[184:187], v[32:47]
	s_waitcnt lgkmcnt(3)
	v_mfma_f32_32x32x16_bf16 v[16:31], v[180:183], v[188:191], v[16:31]
	ds_read_b64_tr_b16 v[154:155], v172 offset:48384
	ds_read_b128 v[156:159], v163 offset:32
	ds_read_b128 v[180:183], v163 offset:4640
	ds_read_b64_tr_b16 v[186:187], v172 offset:48448
	ds_read_b64_tr_b16 v[184:185], v172 offset:46144
	s_waitcnt lgkmcnt(3)
	v_mfma_f32_32x32x16_bf16 v[112:127], v[152:155], v[156:159], v[112:127]
	s_waitcnt lgkmcnt(0)
	v_mfma_f32_32x32x16_bf16 v[96:111], v[184:187], v[156:159], v[96:111]
	v_mfma_f32_32x32x16_bf16 v[80:95], v[152:155], v[180:183], v[80:95]
	v_mfma_f32_32x32x16_bf16 v[64:79], v[184:187], v[180:183], v[64:79]
	ds_read_b128 v[156:159], v163 offset:9248
	ds_read_b128 v[180:183], v163 offset:13856
	ds_write_b128 v179, v[144:147] offset:9216
	s_waitcnt vmcnt(2)
	ds_write_b128 v217, v[148:151] offset:46080
	ds_read_b64_tr_b16 v[144:145], v172 offset:55296
	s_waitcnt lgkmcnt(4)
	v_mfma_f32_32x32x16_bf16 v[48:63], v[152:155], v[156:159], v[48:63]
	v_mfma_f32_32x32x16_bf16 v[32:47], v[184:187], v[156:159], v[32:47]
	s_waitcnt lgkmcnt(3)
	v_mfma_f32_32x32x16_bf16 v[16:31], v[152:155], v[180:183], v[16:31]
	ds_read_b64_tr_b16 v[146:147], v172 offset:57600
	ds_read_b128 v[148:151], v163 offset:64
	ds_read_b128 v[152:155], v163 offset:4672
	ds_read_b64_tr_b16 v[158:159], v172 offset:57664
	ds_read_b64_tr_b16 v[156:157], v172 offset:55360
	v_mfma_f32_32x32x16_bf16 v[0:15], v[218:221], v[188:191], v[0:15]
	s_waitcnt lgkmcnt(3)
	v_mfma_f32_32x32x16_bf16 v[112:127], v[144:147], v[148:151], v[112:127]
	s_waitcnt lgkmcnt(0)
	v_mfma_f32_32x32x16_bf16 v[96:111], v[156:159], v[148:151], v[96:111]
	v_mfma_f32_32x32x16_bf16 v[80:95], v[144:147], v[152:155], v[80:95]
	v_mfma_f32_32x32x16_bf16 v[64:79], v[156:159], v[152:155], v[64:79]
	ds_read_b128 v[148:151], v163 offset:9280
	ds_read_b128 v[152:155], v163 offset:13888
	ds_write_b128 v179, v[136:139] offset:18432
	s_waitcnt vmcnt(1)
	ds_write_b128 v217, v[140:143] offset:55296
	s_waitcnt lgkmcnt(3)
	v_mfma_f32_32x32x16_bf16 v[48:63], v[144:147], v[148:151], v[48:63]
	v_mfma_f32_32x32x16_bf16 v[32:47], v[156:159], v[148:151], v[32:47]
	v_add_u32_e32 v148, 0x9000, v172
	s_waitcnt lgkmcnt(2)
	v_mfma_f32_32x32x16_bf16 v[16:31], v[144:147], v[152:155], v[16:31]
	v_lshl_add_u64 v[144:145], s[94:95], 0, v[160:161]
	v_lshl_add_u64 v[146:147], s[94:95], 0, v[166:167]
	v_lshl_add_u64 v[166:167], v[166:167], 0, s[26:27]
	v_lshl_add_u64 v[160:161], v[160:161], 0, s[24:25]
	v_mfma_f32_32x32x16_bf16 v[0:15], v[184:187], v[180:183], v[0:15]
	ds_read_b64_tr_b16 v[180:181], v172 offset:64512
	ds_read_b64_tr_b16 v[182:183], v148 offset:29952
	ds_read_b128 v[136:139], v163 offset:96
	ds_read_b128 v[140:143], v163 offset:4704
	ds_read_b64_tr_b16 v[186:187], v148 offset:30016
	ds_read_b64_tr_b16 v[184:185], v172 offset:64576
	v_add_co_u32_e32 v148, vcc, s16, v144
	s_nop 1
	v_addc_co_u32_e32 v149, vcc, 0, v145, vcc
	v_add_co_u32_e32 v150, vcc, s19, v146
	s_waitcnt lgkmcnt(3)
	v_mfma_f32_32x32x16_bf16 v[112:127], v[180:183], v[136:139], v[112:127]
	v_addc_co_u32_e32 v151, vcc, 0, v147, vcc
	v_add_co_u32_e32 v192, vcc, s17, v144
	s_nop 1
	v_addc_co_u32_e32 v193, vcc, 0, v145, vcc
	v_add_co_u32_e32 v218, vcc, s18, v146
	s_waitcnt lgkmcnt(0)
	v_mfma_f32_32x32x16_bf16 v[96:111], v[184:187], v[136:139], v[96:111]
	v_addc_co_u32_e32 v219, vcc, 0, v147, vcc
	v_add_co_u32_e32 v220, vcc, s20, v144
	ds_read_b128 v[136:139], v163 offset:9312
	ds_read_b128 v[188:191], v163 offset:13920
	v_addc_co_u32_e32 v221, vcc, 0, v145, vcc
	v_add_co_u32_e32 v222, vcc, s21, v146
	v_mfma_f32_32x32x16_bf16 v[0:15], v[156:159], v[152:155], v[0:15]
	s_nop 0
	v_addc_co_u32_e32 v223, vcc, 0, v147, vcc
	v_add_co_u32_e32 v224, vcc, s22, v144
	global_load_dwordx4 v[152:155], v[148:149], off offset:768
	global_load_dwordx4 v[156:159], v[150:151], off
	v_addc_co_u32_e32 v225, vcc, 0, v145, vcc
	v_add_co_u32_e32 v226, vcc, s23, v146
	v_mfma_f32_32x32x16_bf16 v[80:95], v[180:183], v[140:143], v[80:95]
	s_nop 0
	v_addc_co_u32_e32 v227, vcc, 0, v147, vcc
	v_mfma_f32_32x32x16_bf16 v[64:79], v[184:187], v[140:143], v[64:79]
	s_waitcnt lgkmcnt(1)
	v_mfma_f32_32x32x16_bf16 v[48:63], v[180:183], v[136:139], v[48:63]
	v_mfma_f32_32x32x16_bf16 v[32:47], v[184:187], v[136:139], v[32:47]
	global_load_dwordx4 v[144:147], v[192:193], off offset:768
	global_load_dwordx4 v[148:151], v[218:219], off
	global_load_dwordx4 v[136:139], v[220:221], off offset:768
	global_load_dwordx4 v[140:143], v[222:223], off
	ds_write_b128 v179, v[128:131] offset:27648
	s_waitcnt vmcnt(6)
	ds_write_b128 v217, v[132:135] offset:64512
	global_load_dwordx4 v[128:131], v[224:225], off offset:768
	global_load_dwordx4 v[132:135], v[226:227], off
	s_waitcnt lgkmcnt(0)
	s_barrier
; DI f32x16 mfma32(bf16x8 a, bf16x8 b, f32x16 c) { return __builtin_amdgcn_mfma_f32_32x32x16_bf16(a, b, c, 0, 0, 0); }
; DI s16x4 tr_read(const char* p) { bfx4 r = __builtin_amdgcn_ds_read_tr16_b64_v4bf16((LDS_AS bfx4*)p); return __builtin_bit_cast(s16x4, r); }
; DI bf16x8 cat8(s16x4 lo, s16x4 hi) { return __builtin_shufflevector(lo, hi, 0, 1, 2, 3, 4, 5, 6, 7); }
; template <int BM, class Epi>
; DI void gemm_tile(const bf16_t* __restrict__ A, int lda, const bf16_t* __restrict__ B, int ldb, int K, int row0, int col0, const Epi& epi, char* smem) {
;     ...
;     for (int kt = 0; kt < nk; ++kt) {
;         const char* cur = smem + (kt & 1) * GSTAGE;
;         char* nxt = smem + ((kt & 1) ^ 1) * GSTAGE;
;         const bool w1 = kt + 1 < nk, l2 = kt + 2 < nk;
;         const bf16_t* a2 = ag + (size_t)(kt + 2) * 64; const bf16_t* b2 = bg + (size_t)(kt + 2) * 64 * ldb;
; #pragma unroll
;         for (int s = 0; s < 4; ++s) {
;             bf16x8 xf[MI], wf[2];
; #pragma unroll
;             for (int mi = 0; mi < MI; ++mi) xf[mi] = *(const bf16x8*)(cur + xoff + mi * 32 * GA_S + s * 32);
; #pragma unroll
;             for (int ni = 0; ni < 2; ++ni) {
;                 const char* wp = cur + woff + s * 16 * GB_S + ni * 64;
;                 wf[ni] = cat8(tr_read(wp), tr_read(wp + 4 * GB_S));
;             }
; #pragma unroll
;             for (int mi = 0; mi < MI; ++mi)
; #pragma unroll
;                 for (int ni = 0; ni < 2; ++ni) acc[mi][ni] = mfma32(wf[ni], xf[mi], acc[mi][ni]);
;             if (w1) {
;                 if (s < NA_) *(u32x4*)(nxt + aw + 64 * s * GA_S) = ra[s];
;                 *(u32x4*)(nxt + bw + 16 * s * GB_S) = rb[s];
;             }
;             if (l2) {
;                 if (s < NA_) ra[s] = *(const u32x4*)(a2 + (size_t)(64 * s) * lda);
;                 rb[s] = *(const u32x4*)(b2 + (size_t)(16 * s) * ldb);
;             }
;         }
;         __syncthreads();
;     }
	v_mfma_f32_32x32x16_bf16 v[16:31], v[180:183], v[188:191], v[16:31]
	v_mfma_f32_32x32x16_bf16 v[0:15], v[184:187], v[188:191], v[0:15]
	s_cbranch_scc0 .LBB0_87
	s_add_i32 s0, 0, 0x12000
	v_add3_u32 v167, 0, v165, v174
	v_add3_u32 v166, v177, v162, s0
	v_add3_u32 v172, 0, v175, v176
	ds_read_b128 v[160:163], v167
	ds_read_b128 v[178:181], v167 offset:4608
	ds_read_b128 v[182:185], v167 offset:9216
	ds_read_b128 v[186:189], v167 offset:13824
	ds_read_b64_tr_b16 v[190:191], v172 offset:36864
	ds_read_b64_tr_b16 v[192:193], v172 offset:39168
	ds_read_b64_tr_b16 v[218:219], v172 offset:36928
	ds_read_b64_tr_b16 v[220:221], v172 offset:39232
	s_waitcnt lgkmcnt(2)
	v_mfma_f32_32x32x16_bf16 v[112:127], v[190:193], v[160:163], v[112:127]
	v_add_u32_e32 v164, s0, v164
	s_waitcnt vmcnt(7)
	ds_write_b128 v164, v[152:155]
	s_waitcnt vmcnt(6)
	ds_write_b128 v166, v[156:159] offset:36864
	v_add_u32_e32 v177, 0x9000, v172
	s_add_i32 s2, s2, s14
	s_cmp_gt_i32 s2, 63
	s_waitcnt lgkmcnt(2)
	v_mfma_f32_32x32x16_bf16 v[96:111], v[218:221], v[160:163], v[96:111]
	v_mfma_f32_32x32x16_bf16 v[48:63], v[190:193], v[182:185], v[48:63]
	v_mfma_f32_32x32x16_bf16 v[32:47], v[218:221], v[182:185], v[32:47]
	v_mfma_f32_32x32x16_bf16 v[80:95], v[190:193], v[178:181], v[80:95]
	v_mfma_f32_32x32x16_bf16 v[64:79], v[218:221], v[178:181], v[64:79]
	v_mfma_f32_32x32x16_bf16 v[16:31], v[190:193], v[186:189], v[16:31]
	v_mfma_f32_32x32x16_bf16 v[0:15], v[218:221], v[186:189], v[0:15]
	ds_read_b128 v[152:155], v167 offset:32
	ds_read_b128 v[156:159], v167 offset:4640
	ds_read_b128 v[160:163], v167 offset:9248
	ds_read_b128 v[178:181], v167 offset:13856
	ds_read_b64_tr_b16 v[182:183], v172 offset:46080
	ds_read_b64_tr_b16 v[184:185], v172 offset:48384
	ds_read_b64_tr_b16 v[186:187], v172 offset:46144
	ds_read_b64_tr_b16 v[188:189], v172 offset:48448
	s_waitcnt vmcnt(5)
	ds_write_b128 v164, v[144:147] offset:9216
	s_waitcnt vmcnt(4)
	ds_write_b128 v166, v[148:151] offset:46080
	s_waitcnt lgkmcnt(4)
	v_mfma_f32_32x32x16_bf16 v[112:127], v[182:185], v[152:155], v[112:127]
	s_waitcnt lgkmcnt(2)
	v_mfma_f32_32x32x16_bf16 v[96:111], v[186:189], v[152:155], v[96:111]
	v_mfma_f32_32x32x16_bf16 v[48:63], v[182:185], v[160:163], v[48:63]
	v_mfma_f32_32x32x16_bf16 v[32:47], v[186:189], v[160:163], v[32:47]
	v_mfma_f32_32x32x16_bf16 v[80:95], v[182:185], v[156:159], v[80:95]
	v_mfma_f32_32x32x16_bf16 v[64:79], v[186:189], v[156:159], v[64:79]
	v_mfma_f32_32x32x16_bf16 v[16:31], v[182:185], v[178:181], v[16:31]
	v_mfma_f32_32x32x16_bf16 v[0:15], v[186:189], v[178:181], v[0:15]
	ds_read_b128 v[144:147], v167 offset:64
	ds_read_b128 v[148:151], v167 offset:4672
	ds_read_b128 v[152:155], v167 offset:9280
	ds_read_b128 v[156:159], v167 offset:13888
	ds_read_b64_tr_b16 v[160:161], v172 offset:55296
	ds_read_b64_tr_b16 v[162:163], v172 offset:57600
	ds_read_b64_tr_b16 v[178:179], v172 offset:55360
	ds_read_b64_tr_b16 v[180:181], v172 offset:57664
	s_waitcnt vmcnt(3)
	ds_write_b128 v164, v[136:139] offset:18432
	s_waitcnt vmcnt(2)
	ds_write_b128 v166, v[140:143] offset:55296
	s_waitcnt lgkmcnt(4)
	v_mfma_f32_32x32x16_bf16 v[112:127], v[160:163], v[144:147], v[112:127]
	s_waitcnt lgkmcnt(2)
	v_mfma_f32_32x32x16_bf16 v[96:111], v[178:181], v[144:147], v[96:111]
	v_mfma_f32_32x32x16_bf16 v[48:63], v[160:163], v[152:155], v[48:63]
	v_mfma_f32_32x32x16_bf16 v[32:47], v[178:181], v[152:155], v[32:47]
	v_mfma_f32_32x32x16_bf16 v[80:95], v[160:163], v[148:151], v[80:95]
	v_mfma_f32_32x32x16_bf16 v[64:79], v[178:181], v[148:151], v[64:79]
	v_mfma_f32_32x32x16_bf16 v[16:31], v[160:163], v[156:159], v[16:31]
	v_mfma_f32_32x32x16_bf16 v[0:15], v[178:181], v[156:159], v[0:15]
	ds_read_b128 v[136:139], v167 offset:96
	ds_read_b128 v[140:143], v167 offset:4704
	ds_read_b128 v[144:147], v167 offset:9312
	ds_read_b128 v[148:151], v167 offset:13920
	ds_read_b64_tr_b16 v[152:153], v172 offset:64512
	ds_read_b64_tr_b16 v[154:155], v177 offset:29952
	ds_read_b64_tr_b16 v[156:157], v172 offset:64576
	ds_read_b64_tr_b16 v[158:159], v177 offset:30016
	s_waitcnt vmcnt(1)
	ds_write_b128 v164, v[128:131] offset:27648
	s_waitcnt vmcnt(0)
	ds_write_b128 v166, v[132:135] offset:64512
	s_waitcnt lgkmcnt(0)
	s_barrier
	v_mfma_f32_32x32x16_bf16 v[112:127], v[152:155], v[136:139], v[112:127]
	v_mfma_f32_32x32x16_bf16 v[96:111], v[156:159], v[136:139], v[96:111]
	v_mfma_f32_32x32x16_bf16 v[48:63], v[152:155], v[144:147], v[48:63]
	v_mfma_f32_32x32x16_bf16 v[32:47], v[156:159], v[144:147], v[32:47]
	v_mfma_f32_32x32x16_bf16 v[80:95], v[152:155], v[140:143], v[80:95]
	v_mfma_f32_32x32x16_bf16 v[64:79], v[156:159], v[140:143], v[64:79]
	v_mfma_f32_32x32x16_bf16 v[16:31], v[152:155], v[148:151], v[16:31]
	v_mfma_f32_32x32x16_bf16 v[0:15], v[156:159], v[148:151], v[0:15]
	v_add3_u32 v156, s0, v165, v174
	v_add3_u32 v157, s0, v175, v176
	ds_read_b128 v[128:131], v156 offset:4608
	ds_read_b128 v[132:135], v156 offset:9216
	ds_read_b128 v[136:139], v156 offset:13824
	ds_read_b64_tr_b16 v[140:141], v157 offset:36864
	ds_read_b64_tr_b16 v[142:143], v157 offset:39168
	ds_read_b64_tr_b16 v[144:145], v157 offset:36928
	ds_read_b64_tr_b16 v[146:147], v157 offset:39232
	ds_read_b128 v[148:151], v156
	ds_read_b128 v[152:155], v156 offset:32
	v_add_u32_e32 v158, 0x9000, v157
	v_readlane_b32 s0, v253, 3
	v_readlane_b32 s1, v253, 4
	s_waitcnt lgkmcnt(1)
; DI unsigned pk2(float a, float b) { f32x2 v = {a, b}; bfx2 r = __builtin_convertvector(v, bfx2); return __builtin_bit_cast(unsigned, r); }
; DI f32x16 mfma32(bf16x8 a, bf16x8 b, f32x16 c) { return __builtin_amdgcn_mfma_f32_32x32x16_bf16(a, b, c, 0, 0, 0); }
; DI s16x4 tr_read(const char* p) { bfx4 r = __builtin_amdgcn_ds_read_tr16_b64_v4bf16((LDS_AS bfx4*)p); return __builtin_bit_cast(s16x4, r); }
; template <int BM, class Epi>
; DI void gemm_tile(const bf16_t* __restrict__ A, int lda, const bf16_t* __restrict__ B, int ldb, int K, int row0, int col0, const Epi& epi, char* smem) {
;     ...
;         for (int s = 0; s < 4; ++s) {
;             bf16x8 xf[MI], wf[2];
; #pragma unroll
;             for (int mi = 0; mi < MI; ++mi) xf[mi] = *(const bf16x8*)(cur + xoff + mi * 32 * GA_S + s * 32);
; #pragma unroll
;             for (int ni = 0; ni < 2; ++ni) {
;                 const char* wp = cur + woff + s * 16 * GB_S + ni * 64;
;                 wf[ni] = cat8(tr_read(wp), tr_read(wp + 4 * GB_S));
;             }
; #pragma unroll
;             for (int mi = 0; mi < MI; ++mi)
; #pragma unroll
;                 for (int ni = 0; ni < 2; ++ni) acc[mi][ni] = mfma32(wf[ni], xf[mi], acc[mi][ni]);
;             if (w1) {
;                 if (s < NA_) *(u32x4*)(nxt + aw + 64 * s * GA_S) = ra[s];
;                 *(u32x4*)(nxt + bw + 16 * s * GB_S) = rb[s];
;             }
;             if (l2) {
;                 if (s < NA_) ra[s] = *(const u32x4*)(a2 + (size_t)(64 * s) * lda);
;                 rb[s] = *(const u32x4*)(b2 + (size_t)(16 * s) * ldb);
;             }
;         }
;         __syncthreads();
;     DI void operator()(const f32x16& a0, const f32x16& a1, int row, int cbase, int hh) const {
;         const int s = row < RL ? (row >> 13) : 4;
;         const float* gp = gate + s * 9216;
;         bf16_t* yp = Y + (size_t)row * 1024;
; #pragma unroll
;         for (int ni = 0; ni < 2; ++ni)
; #pragma unroll
;             for (int q4 = 0; q4 < 4; ++q4) {
;                 const int c = cbase + ni * 32 + 8 * q4 + 4 * hh;
;                 const f32x4 g = *(const f32x4*)(gp + c);
;                 const f32x16& v = ni ? a1 : a0;
;                 u32x2 w; w.x = pk2(coef * g[0] * v[4 * q4], coef * g[1] * v[4 * q4 + 1]); w.y = pk2(coef * g[2] * v[4 * q4 + 2], coef * g[3] * v[4 * q4 + 3]);
;                 *(u32x2*)(yp + c) = w;
;             }
	v_mfma_f32_32x32x16_bf16 v[112:127], v[140:143], v[148:151], v[112:127]
	v_mfma_f32_32x32x16_bf16 v[96:111], v[144:147], v[148:151], v[96:111]
	v_mfma_f32_32x32x16_bf16 v[48:63], v[140:143], v[132:135], v[48:63]
	v_mfma_f32_32x32x16_bf16 v[32:47], v[144:147], v[132:135], v[32:47]
	v_mfma_f32_32x32x16_bf16 v[80:95], v[140:143], v[128:131], v[80:95]
	v_mfma_f32_32x32x16_bf16 v[64:79], v[144:147], v[128:131], v[64:79]
	v_mfma_f32_32x32x16_bf16 v[16:31], v[140:143], v[136:139], v[16:31]
	v_mfma_f32_32x32x16_bf16 v[0:15], v[144:147], v[136:139], v[0:15]
	ds_read_b128 v[128:131], v156 offset:4640
	ds_read_b128 v[132:135], v156 offset:9248
	ds_read_b128 v[136:139], v156 offset:13856
	ds_read_b64_tr_b16 v[140:141], v157 offset:46080
	ds_read_b64_tr_b16 v[142:143], v157 offset:48384
	ds_read_b64_tr_b16 v[144:145], v157 offset:46144
	ds_read_b64_tr_b16 v[146:147], v157 offset:48448
	s_waitcnt lgkmcnt(2)
	v_mfma_f32_32x32x16_bf16 v[112:127], v[140:143], v[152:155], v[112:127]
	s_waitcnt lgkmcnt(0)
	v_mfma_f32_32x32x16_bf16 v[96:111], v[144:147], v[152:155], v[96:111]
	v_mfma_f32_32x32x16_bf16 v[48:63], v[140:143], v[132:135], v[48:63]
	v_mfma_f32_32x32x16_bf16 v[32:47], v[144:147], v[132:135], v[32:47]
	v_mfma_f32_32x32x16_bf16 v[80:95], v[140:143], v[128:131], v[80:95]
	v_mfma_f32_32x32x16_bf16 v[64:79], v[144:147], v[128:131], v[64:79]
	v_mfma_f32_32x32x16_bf16 v[16:31], v[140:143], v[136:139], v[16:31]
	v_mfma_f32_32x32x16_bf16 v[0:15], v[144:147], v[136:139], v[0:15]
	ds_read_b128 v[128:131], v156 offset:64
	ds_read_b128 v[132:135], v156 offset:4672
	ds_read_b128 v[136:139], v156 offset:9280
	ds_read_b128 v[140:143], v156 offset:13888
	ds_read_b64_tr_b16 v[144:145], v157 offset:55296
	ds_read_b64_tr_b16 v[146:147], v157 offset:57600
	ds_read_b64_tr_b16 v[148:149], v157 offset:55360
	ds_read_b64_tr_b16 v[150:151], v157 offset:57664
	s_waitcnt lgkmcnt(2)
	v_mfma_f32_32x32x16_bf16 v[112:127], v[144:147], v[128:131], v[112:127]
	s_waitcnt lgkmcnt(0)
	v_mfma_f32_32x32x16_bf16 v[96:111], v[148:151], v[128:131], v[96:111]
	v_mfma_f32_32x32x16_bf16 v[48:63], v[144:147], v[136:139], v[48:63]
	v_mfma_f32_32x32x16_bf16 v[32:47], v[148:151], v[136:139], v[32:47]
	v_mfma_f32_32x32x16_bf16 v[80:95], v[144:147], v[132:135], v[80:95]
	v_mfma_f32_32x32x16_bf16 v[64:79], v[148:151], v[132:135], v[64:79]
	v_mfma_f32_32x32x16_bf16 v[16:31], v[144:147], v[140:143], v[16:31]
	v_mfma_f32_32x32x16_bf16 v[0:15], v[148:151], v[140:143], v[0:15]
	ds_read_b128 v[128:131], v156 offset:96
	ds_read_b128 v[132:135], v156 offset:4704
	ds_read_b128 v[136:139], v156 offset:9312
	ds_read_b128 v[140:143], v156 offset:13920
	ds_read_b64_tr_b16 v[144:145], v157 offset:64512
	ds_read_b64_tr_b16 v[146:147], v158 offset:29952
	ds_read_b64_tr_b16 v[148:149], v157 offset:64576
	ds_read_b64_tr_b16 v[150:151], v158 offset:30016
	s_waitcnt lgkmcnt(0)
	s_barrier
	v_mfma_f32_32x32x16_bf16 v[112:127], v[144:147], v[128:131], v[112:127]
	v_mfma_f32_32x32x16_bf16 v[96:111], v[148:151], v[128:131], v[96:111]
	v_or_b32_e32 v128, s15, v169
	v_and_b32_e32 v129, 0xc0, v168
	v_add_u32_e32 v128, v128, v171
	v_lshlrev_b32_e32 v130, 2, v170
	v_mfma_f32_32x32x16_bf16 v[48:63], v[144:147], v[136:139], v[48:63]
	v_mfma_f32_32x32x16_bf16 v[32:47], v[148:151], v[136:139], v[32:47]
	v_or3_b32 v136, v130, v129, s10
	v_min_i32_e32 v129, 0x8000, v128
	v_ashrrev_i32_e32 v129, 13, v129
	v_mul_i32_i24_e32 v130, 0x2400, v129
	v_ashrrev_i32_e32 v131, 31, v130
	v_ashrrev_i32_e32 v129, 31, v128
	v_ashrrev_i32_e32 v137, 31, v136
	v_mfma_f32_32x32x16_bf16 v[80:95], v[144:147], v[132:135], v[80:95]
	v_mfma_f32_32x32x16_bf16 v[64:79], v[148:151], v[132:135], v[64:79]
	v_lshl_add_u64 v[132:133], v[130:131], 2, s[4:5]
	v_lshlrev_b64 v[130:131], 11, v[128:129]
	v_lshl_add_u64 v[138:139], s[0:1], 0, v[130:131]
	v_lshlrev_b64 v[130:131], 2, v[136:137]
	v_mfma_f32_32x32x16_bf16 v[16:31], v[144:147], v[140:143], v[16:31]
	v_mfma_f32_32x32x16_bf16 v[0:15], v[148:151], v[140:143], v[0:15]
	v_lshl_add_u64 v[140:141], v[132:133], 0, v[130:131]
	global_load_dwordx4 v[228:231], v[140:141], off
	global_load_dwordx4 v[232:235], v[140:141], off offset:32
	global_load_dwordx4 v[236:239], v[140:141], off offset:64
	global_load_dwordx4 v[240:243], v[140:141], off offset:96
	s_waitcnt vmcnt(0)
	v_mul_f32_e64 v112, v112, v228
	v_mul_f32_e64 v113, v113, v229
	v_cvt_pk_bf16_f32 v132, v112, v113
	v_pk_mul_f32 v[112:113], v[114:115], v[230:231]
	s_nop 0
	v_cvt_pk_bf16_f32 v133, v112, v113
	v_lshlrev_b64 v[112:113], 1, v[136:137]
	v_lshl_add_u64 v[136:137], v[138:139], 0, v[112:113]
	global_store_dwordx2 v[136:137], v[132:133], off
	v_pk_mul_f32 v[114:115], v[116:117], v[232:233]
	v_pk_mul_f32 v[116:117], v[118:119], v[234:235]
	v_cvt_pk_bf16_f32 v114, v114, v115
	v_cvt_pk_bf16_f32 v115, v116, v117
	global_store_dwordx2 v[136:137], v[114:115], off offset:16
	v_pk_mul_f32 v[114:115], v[120:121], v[236:237]
	v_pk_mul_f32 v[116:117], v[122:123], v[238:239]
	v_cvt_pk_bf16_f32 v114, v114, v115
	v_cvt_pk_bf16_f32 v115, v116, v117
	global_store_dwordx2 v[136:137], v[114:115], off offset:32
	v_pk_mul_f32 v[114:115], v[124:125], v[240:241]
	v_pk_mul_f32 v[116:117], v[126:127], v[242:243]
	v_cvt_pk_bf16_f32 v114, v114, v115
	v_cvt_pk_bf16_f32 v115, v116, v117
	global_store_dwordx2 v[136:137], v[114:115], off offset:48
	global_load_dwordx4 v[228:231], v[140:141], off offset:128
	global_load_dwordx4 v[232:235], v[140:141], off offset:160
	global_load_dwordx4 v[236:239], v[140:141], off offset:192
	global_load_dwordx4 v[240:243], v[140:141], off offset:224
	s_waitcnt vmcnt(0)
; DI unsigned pk2(float a, float b) { f32x2 v = {a, b}; bfx2 r = __builtin_convertvector(v, bfx2); return __builtin_bit_cast(unsigned, r); }
;     DI void operator()(const f32x16& a0, const f32x16& a1, int row, int cbase, int hh) const {
;         const int s = row < RL ? (row >> 13) : 4;
;         const float* gp = gate + s * 9216;
;         bf16_t* yp = Y + (size_t)row * 1024;
; #pragma unroll
;         for (int ni = 0; ni < 2; ++ni)
; #pragma unroll
;             for (int q4 = 0; q4 < 4; ++q4) {
;                 const int c = cbase + ni * 32 + 8 * q4 + 4 * hh;
;                 const f32x4 g = *(const f32x4*)(gp + c);
;                 const f32x16& v = ni ? a1 : a0;
;                 u32x2 w; w.x = pk2(coef * g[0] * v[4 * q4], coef * g[1] * v[4 * q4 + 1]); w.y = pk2(coef * g[2] * v[4 * q4 + 2], coef * g[3] * v[4 * q4 + 3]);
;                 *(u32x2*)(yp + c) = w;
;             }
;     }
	v_pk_mul_f32 v[96:97], v[96:97], v[228:229]
	v_pk_mul_f32 v[98:99], v[98:99], v[230:231]
	v_cvt_pk_bf16_f32 v96, v96, v97
	v_cvt_pk_bf16_f32 v97, v98, v99
	global_store_dwordx2 v[136:137], v[96:97], off offset:64
	v_pk_mul_f32 v[96:97], v[100:101], v[232:233]
	v_pk_mul_f32 v[98:99], v[102:103], v[234:235]
	v_cvt_pk_bf16_f32 v96, v96, v97
	v_cvt_pk_bf16_f32 v97, v98, v99
	global_store_dwordx2 v[136:137], v[96:97], off offset:80
	v_pk_mul_f32 v[96:97], v[104:105], v[236:237]
	v_pk_mul_f32 v[98:99], v[106:107], v[238:239]
	v_cvt_pk_bf16_f32 v96, v96, v97
	v_cvt_pk_bf16_f32 v97, v98, v99
	global_store_dwordx2 v[136:137], v[96:97], off offset:96
	v_pk_mul_f32 v[96:97], v[108:109], v[240:241]
	v_pk_mul_f32 v[98:99], v[110:111], v[242:243]
	v_cvt_pk_bf16_f32 v96, v96, v97
	v_cvt_pk_bf16_f32 v97, v98, v99
	global_store_dwordx2 v[136:137], v[96:97], off offset:112
	v_or_b32_e32 v96, 32, v128
	v_min_i32_e32 v97, 0x8000, v96
	v_ashrrev_i32_e32 v97, 13, v97
	v_mul_i32_i24_e32 v98, 0x2400, v97
	v_ashrrev_i32_e32 v99, 31, v98
	v_lshl_add_u64 v[98:99], v[98:99], 2, s[4:5]
	v_ashrrev_i32_e32 v97, 31, v96
	v_lshlrev_b64 v[96:97], 11, v[96:97]
	v_lshl_add_u64 v[102:103], v[98:99], 0, v[130:131]
	v_lshl_add_u64 v[100:101], s[0:1], 0, v[96:97]
	global_load_dwordx4 v[228:231], v[102:103], off
	global_load_dwordx4 v[232:235], v[102:103], off offset:32
	global_load_dwordx4 v[236:239], v[102:103], off offset:64
	global_load_dwordx4 v[240:243], v[102:103], off offset:96
	s_waitcnt vmcnt(0)
	v_pk_mul_f32 v[80:81], v[80:81], v[228:229]
	v_pk_mul_f32 v[82:83], v[82:83], v[230:231]
	v_cvt_pk_bf16_f32 v80, v80, v81
	v_cvt_pk_bf16_f32 v81, v82, v83
	v_lshl_add_u64 v[96:97], v[100:101], 0, v[112:113]
	global_store_dwordx2 v[96:97], v[80:81], off
	v_pk_mul_f32 v[80:81], v[84:85], v[232:233]
	v_pk_mul_f32 v[82:83], v[86:87], v[234:235]
	v_cvt_pk_bf16_f32 v80, v80, v81
	v_cvt_pk_bf16_f32 v81, v82, v83
	global_store_dwordx2 v[96:97], v[80:81], off offset:16
	v_pk_mul_f32 v[80:81], v[88:89], v[236:237]
	v_pk_mul_f32 v[82:83], v[90:91], v[238:239]
	v_cvt_pk_bf16_f32 v80, v80, v81
	v_cvt_pk_bf16_f32 v81, v82, v83
	global_store_dwordx2 v[96:97], v[80:81], off offset:32
	v_pk_mul_f32 v[80:81], v[92:93], v[240:241]
	v_pk_mul_f32 v[82:83], v[94:95], v[242:243]
	v_cvt_pk_bf16_f32 v80, v80, v81
	v_cvt_pk_bf16_f32 v81, v82, v83
	global_store_dwordx2 v[96:97], v[80:81], off offset:48
	global_load_dwordx4 v[228:231], v[102:103], off offset:128
	global_load_dwordx4 v[232:235], v[102:103], off offset:160
	global_load_dwordx4 v[236:239], v[102:103], off offset:192
	global_load_dwordx4 v[240:243], v[102:103], off offset:224
	s_waitcnt vmcnt(0)
	v_pk_mul_f32 v[64:65], v[64:65], v[228:229]
	v_pk_mul_f32 v[66:67], v[66:67], v[230:231]
	v_cvt_pk_bf16_f32 v64, v64, v65
	v_cvt_pk_bf16_f32 v65, v66, v67
	global_store_dwordx2 v[96:97], v[64:65], off offset:64
	v_pk_mul_f32 v[64:65], v[68:69], v[232:233]
	v_pk_mul_f32 v[66:67], v[70:71], v[234:235]
	v_cvt_pk_bf16_f32 v64, v64, v65
	v_cvt_pk_bf16_f32 v65, v66, v67
	global_store_dwordx2 v[96:97], v[64:65], off offset:80
	v_pk_mul_f32 v[64:65], v[72:73], v[236:237]
	v_pk_mul_f32 v[66:67], v[74:75], v[238:239]
	v_cvt_pk_bf16_f32 v64, v64, v65
	v_cvt_pk_bf16_f32 v65, v66, v67
	global_store_dwordx2 v[96:97], v[64:65], off offset:96
	v_pk_mul_f32 v[64:65], v[76:77], v[240:241]
	v_pk_mul_f32 v[66:67], v[78:79], v[242:243]
	v_cvt_pk_bf16_f32 v64, v64, v65
	v_cvt_pk_bf16_f32 v65, v66, v67
	global_store_dwordx2 v[96:97], v[64:65], off offset:112
	v_or_b32_e32 v64, 64, v128
	v_min_i32_e32 v65, 0x8000, v64
	v_ashrrev_i32_e32 v65, 13, v65
	v_mul_i32_i24_e32 v66, 0x2400, v65
	v_ashrrev_i32_e32 v67, 31, v66
	v_lshl_add_u64 v[66:67], v[66:67], 2, s[4:5]
	v_ashrrev_i32_e32 v65, 31, v64
	v_lshlrev_b64 v[64:65], 11, v[64:65]
	v_lshl_add_u64 v[70:71], v[66:67], 0, v[130:131]
	v_lshl_add_u64 v[68:69], s[0:1], 0, v[64:65]
	global_load_dwordx4 v[228:231], v[70:71], off
	global_load_dwordx4 v[232:235], v[70:71], off offset:32
	global_load_dwordx4 v[236:239], v[70:71], off offset:64
	global_load_dwordx4 v[240:243], v[70:71], off offset:96
	s_waitcnt vmcnt(0)
; DI unsigned pk2(float a, float b) { f32x2 v = {a, b}; bfx2 r = __builtin_convertvector(v, bfx2); return __builtin_bit_cast(unsigned, r); }
;     DI void operator()(const f32x16& a0, const f32x16& a1, int row, int cbase, int hh) const {
;         const int s = row < RL ? (row >> 13) : 4;
;         const float* gp = gate + s * 9216;
;         bf16_t* yp = Y + (size_t)row * 1024;
; #pragma unroll
;         for (int ni = 0; ni < 2; ++ni)
; #pragma unroll
;             for (int q4 = 0; q4 < 4; ++q4) {
;                 const int c = cbase + ni * 32 + 8 * q4 + 4 * hh;
;                 const f32x4 g = *(const f32x4*)(gp + c);
;                 const f32x16& v = ni ? a1 : a0;
;                 u32x2 w; w.x = pk2(coef * g[0] * v[4 * q4], coef * g[1] * v[4 * q4 + 1]); w.y = pk2(coef * g[2] * v[4 * q4 + 2], coef * g[3] * v[4 * q4 + 3]);
;                 *(u32x2*)(yp + c) = w;
;             }
;     }
	v_pk_mul_f32 v[48:49], v[48:49], v[228:229]
	v_pk_mul_f32 v[50:51], v[50:51], v[230:231]
	v_cvt_pk_bf16_f32 v48, v48, v49
	v_cvt_pk_bf16_f32 v49, v50, v51
	v_lshl_add_u64 v[64:65], v[68:69], 0, v[112:113]
	global_store_dwordx2 v[64:65], v[48:49], off
	v_pk_mul_f32 v[48:49], v[52:53], v[232:233]
	v_pk_mul_f32 v[50:51], v[54:55], v[234:235]
	v_cvt_pk_bf16_f32 v48, v48, v49
	v_cvt_pk_bf16_f32 v49, v50, v51
	global_store_dwordx2 v[64:65], v[48:49], off offset:16
	v_pk_mul_f32 v[48:49], v[56:57], v[236:237]
	v_pk_mul_f32 v[50:51], v[58:59], v[238:239]
	v_cvt_pk_bf16_f32 v48, v48, v49
	v_cvt_pk_bf16_f32 v49, v50, v51
	global_store_dwordx2 v[64:65], v[48:49], off offset:32
	v_pk_mul_f32 v[48:49], v[60:61], v[240:241]
	v_pk_mul_f32 v[50:51], v[62:63], v[242:243]
	v_cvt_pk_bf16_f32 v48, v48, v49
	v_cvt_pk_bf16_f32 v49, v50, v51
	global_store_dwordx2 v[64:65], v[48:49], off offset:48
	global_load_dwordx4 v[228:231], v[70:71], off offset:128
	global_load_dwordx4 v[232:235], v[70:71], off offset:160
	global_load_dwordx4 v[236:239], v[70:71], off offset:192
	global_load_dwordx4 v[240:243], v[70:71], off offset:224
	s_waitcnt vmcnt(0)
	v_pk_mul_f32 v[32:33], v[32:33], v[228:229]
	v_pk_mul_f32 v[34:35], v[34:35], v[230:231]
	v_cvt_pk_bf16_f32 v32, v32, v33
	v_cvt_pk_bf16_f32 v33, v34, v35
	global_store_dwordx2 v[64:65], v[32:33], off offset:64
	v_pk_mul_f32 v[32:33], v[36:37], v[232:233]
	v_pk_mul_f32 v[34:35], v[38:39], v[234:235]
	v_cvt_pk_bf16_f32 v32, v32, v33
	v_cvt_pk_bf16_f32 v33, v34, v35
	global_store_dwordx2 v[64:65], v[32:33], off offset:80
	v_pk_mul_f32 v[32:33], v[40:41], v[236:237]
	v_pk_mul_f32 v[34:35], v[42:43], v[238:239]
	v_cvt_pk_bf16_f32 v32, v32, v33
	v_cvt_pk_bf16_f32 v33, v34, v35
	global_store_dwordx2 v[64:65], v[32:33], off offset:96
	v_pk_mul_f32 v[32:33], v[44:45], v[240:241]
	v_pk_mul_f32 v[34:35], v[46:47], v[242:243]
	v_cvt_pk_bf16_f32 v32, v32, v33
	v_cvt_pk_bf16_f32 v33, v34, v35
	global_store_dwordx2 v[64:65], v[32:33], off offset:112
	v_or_b32_e32 v32, 0x60, v128
	v_min_i32_e32 v33, 0x8000, v32
	v_ashrrev_i32_e32 v33, 13, v33
	v_mul_i32_i24_e32 v34, 0x2400, v33
	v_ashrrev_i32_e32 v35, 31, v34
	v_lshl_add_u64 v[34:35], v[34:35], 2, s[4:5]
	v_ashrrev_i32_e32 v33, 31, v32
	v_lshlrev_b64 v[32:33], 11, v[32:33]
	v_lshl_add_u64 v[38:39], v[34:35], 0, v[130:131]
	v_lshl_add_u64 v[36:37], s[0:1], 0, v[32:33]
	global_load_dwordx4 v[228:231], v[38:39], off
	global_load_dwordx4 v[232:235], v[38:39], off offset:32
	global_load_dwordx4 v[236:239], v[38:39], off offset:64
	global_load_dwordx4 v[240:243], v[38:39], off offset:96
	s_waitcnt vmcnt(0)
	v_pk_mul_f32 v[16:17], v[16:17], v[228:229]
	v_pk_mul_f32 v[18:19], v[18:19], v[230:231]
	v_cvt_pk_bf16_f32 v16, v16, v17
	v_cvt_pk_bf16_f32 v17, v18, v19
	v_lshl_add_u64 v[32:33], v[36:37], 0, v[112:113]
	global_store_dwordx2 v[32:33], v[16:17], off
	v_pk_mul_f32 v[16:17], v[20:21], v[232:233]
	v_pk_mul_f32 v[18:19], v[22:23], v[234:235]
	v_cvt_pk_bf16_f32 v16, v16, v17
	v_cvt_pk_bf16_f32 v17, v18, v19
	global_store_dwordx2 v[32:33], v[16:17], off offset:16
	v_pk_mul_f32 v[16:17], v[24:25], v[236:237]
	v_pk_mul_f32 v[18:19], v[26:27], v[238:239]
	v_cvt_pk_bf16_f32 v16, v16, v17
	v_cvt_pk_bf16_f32 v17, v18, v19
	global_store_dwordx2 v[32:33], v[16:17], off offset:32
	v_pk_mul_f32 v[16:17], v[28:29], v[240:241]
	v_pk_mul_f32 v[18:19], v[30:31], v[242:243]
	v_cvt_pk_bf16_f32 v16, v16, v17
	v_cvt_pk_bf16_f32 v17, v18, v19
	global_store_dwordx2 v[32:33], v[16:17], off offset:48
	global_load_dwordx4 v[228:231], v[38:39], off offset:128
	global_load_dwordx4 v[232:235], v[38:39], off offset:160
	global_load_dwordx4 v[236:239], v[38:39], off offset:192
	global_load_dwordx4 v[240:243], v[38:39], off offset:224
	s_waitcnt vmcnt(0)
	v_pk_mul_f32 v[0:1], v[0:1], v[228:229]
	v_pk_mul_f32 v[2:3], v[2:3], v[230:231]
	v_cvt_pk_bf16_f32 v0, v0, v1
	v_cvt_pk_bf16_f32 v1, v2, v3
	global_store_dwordx2 v[32:33], v[0:1], off offset:64
	v_pk_mul_f32 v[0:1], v[4:5], v[232:233]
	v_pk_mul_f32 v[2:3], v[6:7], v[234:235]
	v_cvt_pk_bf16_f32 v0, v0, v1
	v_cvt_pk_bf16_f32 v1, v2, v3
	global_store_dwordx2 v[32:33], v[0:1], off offset:80
	v_pk_mul_f32 v[0:1], v[8:9], v[236:237]
	v_pk_mul_f32 v[2:3], v[10:11], v[238:239]
	v_cvt_pk_bf16_f32 v0, v0, v1
	v_cvt_pk_bf16_f32 v1, v2, v3
	global_store_dwordx2 v[32:33], v[0:1], off offset:96
	v_pk_mul_f32 v[0:1], v[12:13], v[240:241]
	v_pk_mul_f32 v[2:3], v[14:15], v[242:243]
	v_cvt_pk_bf16_f32 v0, v0, v1
	v_cvt_pk_bf16_f32 v1, v2, v3
	global_store_dwordx2 v[32:33], v[0:1], off offset:112
	s_cbranch_scc0 .LBB0_82

; DI f32x16 mfma32(bf16x8 a, bf16x8 b, f32x16 c) { return __builtin_amdgcn_mfma_f32_32x32x16_bf16(a, b, c, 0, 0, 0); }
; DI s16x4 tr_read(const char* p) { bfx4 r = __builtin_amdgcn_ds_read_tr16_b64_v4bf16((LDS_AS bfx4*)p); return __builtin_bit_cast(s16x4, r); }
; DI bf16x8 cat8(s16x4 lo, s16x4 hi) { return __builtin_shufflevector(lo, hi, 0, 1, 2, 3, 4, 5, 6, 7); }
; template <int BM, class Epi>
; DI void gemm_tile(const bf16_t* __restrict__ A, int lda, const bf16_t* __restrict__ B, int ldb, int K, int row0, int col0, const Epi& epi, char* smem) {
;     ...
;     for (int kt = 0; kt < nk; ++kt) {
;         const char* cur = smem + (kt & 1) * GSTAGE;
;         char* nxt = smem + ((kt & 1) ^ 1) * GSTAGE;
;         const bool w1 = kt + 1 < nk, l2 = kt + 2 < nk;
;         const bf16_t* a2 = ag + (size_t)(kt + 2) * 64; const bf16_t* b2 = bg + (size_t)(kt + 2) * 64 * ldb;
; #pragma unroll
;         for (int s = 0; s < 4; ++s) {
;             bf16x8 xf[MI], wf[2];
; #pragma unroll
;             for (int mi = 0; mi < MI; ++mi) xf[mi] = *(const bf16x8*)(cur + xoff + mi * 32 * GA_S + s * 32);
; #pragma unroll
;             for (int ni = 0; ni < 2; ++ni) {
;                 const char* wp = cur + woff + s * 16 * GB_S + ni * 64;
;                 wf[ni] = cat8(tr_read(wp), tr_read(wp + 4 * GB_S));
;             }
; #pragma unroll
;             for (int mi = 0; mi < MI; ++mi)
; #pragma unroll
;                 for (int ni = 0; ni < 2; ++ni) acc[mi][ni] = mfma32(wf[ni], xf[mi], acc[mi][ni]);
;             if (w1) {
;                 if (s < NA_) *(u32x4*)(nxt + aw + 64 * s * GA_S) = ra[s];
;                 *(u32x4*)(nxt + bw + 16 * s * GB_S) = rb[s];
;             }
;             if (l2) {
;                 if (s < NA_) ra[s] = *(const u32x4*)(a2 + (size_t)(64 * s) * lda);
;                 rb[s] = *(const u32x4*)(b2 + (size_t)(16 * s) * ldb);
;             }
;         }
;         __syncthreads();
;     }
.LBB0_91:
	s_and_b32 s2, s1, 1
	s_mul_i32 s3, s2, 0x12000
	s_add_i32 s3, s3, 0
	v_add3_u32 v105, s3, v101, v102
	s_xor_b32 s2, s2, 1
	v_add3_u32 v91, s3, v93, v100
	ds_read_b64_tr_b16 v[106:107], v105 offset:18432
	ds_read_b64_tr_b16 v[108:109], v105 offset:20736
	ds_read_b128 v[110:113], v91
	ds_read_b128 v[114:117], v91 offset:4608
	ds_read_b64_tr_b16 v[120:121], v105 offset:20800
	ds_read_b64_tr_b16 v[118:119], v105 offset:18496
	s_mul_i32 s2, s2, 0x12000
	s_add_i32 s2, s2, 0
	v_add_u32_e32 v122, s2, v92
	v_add_u32_e32 v124, s2, v104
	s_waitcnt vmcnt(5)
	ds_write_b128 v122, v[80:83]
	s_waitcnt vmcnt(3)
	ds_write_b128 v124, v[84:87] offset:18432
	ds_read_b64_tr_b16 v[80:81], v105 offset:27648
	s_waitcnt lgkmcnt(6)
	v_mfma_f32_32x32x16_bf16 v[48:63], v[106:109], v[110:113], v[48:63]
	s_add_i32 s1, s1, 1
	s_cmp_eq_u32 s1, 14
	s_waitcnt lgkmcnt(3)
	v_mfma_f32_32x32x16_bf16 v[32:47], v[118:121], v[110:113], v[32:47]
	v_mfma_f32_32x32x16_bf16 v[16:31], v[106:109], v[114:117], v[16:31]
	ds_read_b64_tr_b16 v[82:83], v105 offset:29952
	ds_read_b128 v[84:87], v91 offset:32
	ds_read_b128 v[106:109], v91 offset:4640
	ds_read_b64_tr_b16 v[112:113], v105 offset:30016
	ds_read_b64_tr_b16 v[110:111], v105 offset:27712
	ds_write_b128 v122, v[72:75] offset:9216
	s_waitcnt vmcnt(2)
	ds_write_b128 v124, v[76:79] offset:27648
	ds_read_b64_tr_b16 v[72:73], v105 offset:36864
	v_mfma_f32_32x32x16_bf16 v[0:15], v[118:121], v[114:117], v[0:15]
	v_lshl_add_u64 v[118:119], s[94:95], 0, v[94:95]
	v_lshl_add_u64 v[94:95], v[94:95], 0, s[22:23]
	s_waitcnt lgkmcnt(6)
	v_mfma_f32_32x32x16_bf16 v[48:63], v[80:83], v[84:87], v[48:63]
	s_waitcnt lgkmcnt(3)
	v_mfma_f32_32x32x16_bf16 v[32:47], v[110:113], v[84:87], v[32:47]
	v_mfma_f32_32x32x16_bf16 v[16:31], v[80:83], v[106:109], v[16:31]
	ds_read_b64_tr_b16 v[74:75], v105 offset:39168
	ds_read_b128 v[76:79], v91 offset:64
	ds_read_b128 v[80:83], v91 offset:4672
	ds_read_b64_tr_b16 v[86:87], v105 offset:39232
	ds_read_b64_tr_b16 v[84:85], v105 offset:36928
	s_waitcnt vmcnt(1)
	ds_write_b128 v124, v[68:71] offset:36864
	v_mfma_f32_32x32x16_bf16 v[0:15], v[110:113], v[106:109], v[0:15]
	v_lshl_add_u64 v[106:107], s[94:95], 0, v[88:89]
	v_lshl_add_u64 v[88:89], v[88:89], 0, s[20:21]
	s_waitcnt lgkmcnt(4)
	v_mfma_f32_32x32x16_bf16 v[48:63], v[72:75], v[76:79], v[48:63]
	s_waitcnt lgkmcnt(1)
	v_mfma_f32_32x32x16_bf16 v[32:47], v[84:87], v[76:79], v[32:47]
	v_add_co_u32_e32 v76, vcc, s15, v106
	s_nop 1
	v_addc_co_u32_e32 v77, vcc, 0, v107, vcc
	v_add_co_u32_e32 v78, vcc, s14, v118
	v_mfma_f32_32x32x16_bf16 v[16:31], v[72:75], v[80:83], v[16:31]
	s_nop 0
	v_addc_co_u32_e32 v79, vcc, 0, v119, vcc
	v_add_co_u32_e32 v72, vcc, s16, v106
	s_nop 1
	v_addc_co_u32_e32 v73, vcc, 0, v107, vcc
	ds_read_b64_tr_b16 v[106:107], v105 offset:46080
	ds_read_b64_tr_b16 v[108:109], v105 offset:48384
	ds_read_b128 v[68:71], v91 offset:96
	ds_read_b128 v[110:113], v91 offset:4704
	ds_read_b64_tr_b16 v[116:117], v105 offset:48448
	ds_read_b64_tr_b16 v[114:115], v105 offset:46144
	v_add_co_u32_e32 v120, vcc, s17, v118
	v_mfma_f32_32x32x16_bf16 v[0:15], v[84:87], v[80:83], v[0:15]
	s_nop 0
	v_addc_co_u32_e32 v121, vcc, 0, v119, vcc
	v_add_co_u32_e32 v122, vcc, s18, v118
	s_nop 1
	v_addc_co_u32_e32 v123, vcc, 0, v119, vcc
	s_waitcnt lgkmcnt(3)
	v_mfma_f32_32x32x16_bf16 v[48:63], v[106:109], v[68:71], v[48:63]
	v_add_co_u32_e32 v118, vcc, s19, v118
	s_nop 1
	v_addc_co_u32_e32 v119, vcc, 0, v119, vcc
	s_waitcnt lgkmcnt(0)
	v_mfma_f32_32x32x16_bf16 v[32:47], v[114:117], v[68:71], v[32:47]
	global_load_dwordx4 v[80:83], v[76:77], off offset:768
	global_load_dwordx4 v[84:87], v[78:79], off
	s_nop 0
	global_load_dwordx4 v[72:75], v[72:73], off offset:768
	s_nop 0
	global_load_dwordx4 v[76:79], v[120:121], off
	global_load_dwordx4 v[68:71], v[122:123], off
	s_waitcnt vmcnt(5)
	ds_write_b128 v124, v[64:67] offset:46080
	global_load_dwordx4 v[64:67], v[118:119], off
	s_waitcnt lgkmcnt(0)
	s_barrier
	v_mfma_f32_32x32x16_bf16 v[16:31], v[106:109], v[110:113], v[16:31]
	v_mfma_f32_32x32x16_bf16 v[0:15], v[114:117], v[110:113], v[0:15]
	s_cbranch_scc0 .LBB0_91
	s_add_i32 s1, 0, 0x12000
	v_add3_u32 v95, 0, v93, v100
	v_add3_u32 v94, v103, v90, s1
	v_add3_u32 v103, 0, v101, v102
	ds_read_b128 v[88:91], v95
	ds_read_b128 v[104:107], v95 offset:4608
	ds_read_b64_tr_b16 v[108:109], v103 offset:18432
	ds_read_b64_tr_b16 v[110:111], v103 offset:20736
	ds_read_b64_tr_b16 v[112:113], v103 offset:18496
	ds_read_b64_tr_b16 v[114:115], v103 offset:20800
	s_waitcnt lgkmcnt(2)
	v_mfma_f32_32x32x16_bf16 v[48:63], v[108:111], v[88:91], v[48:63]
	v_add_u32_e32 v92, s1, v92
	s_waitcnt vmcnt(5)
	ds_write_b128 v92, v[80:83]
	s_waitcnt vmcnt(4)
	ds_write_b128 v94, v[84:87] offset:18432
	s_add_i32 s12, s12, s13
	s_waitcnt lgkmcnt(2)
	v_mfma_f32_32x32x16_bf16 v[32:47], v[112:115], v[88:91], v[32:47]
	v_mfma_f32_32x32x16_bf16 v[16:31], v[108:111], v[104:107], v[16:31]
	v_mfma_f32_32x32x16_bf16 v[0:15], v[112:115], v[104:107], v[0:15]
	ds_read_b128 v[80:83], v95 offset:32
	ds_read_b128 v[84:87], v95 offset:4640
	ds_read_b64_tr_b16 v[88:89], v103 offset:27648
	ds_read_b64_tr_b16 v[90:91], v103 offset:29952
	ds_read_b64_tr_b16 v[104:105], v103 offset:27712
	ds_read_b64_tr_b16 v[106:107], v103 offset:30016
	s_waitcnt vmcnt(3)
	ds_write_b128 v92, v[72:75] offset:9216
	s_waitcnt vmcnt(2)
	ds_write_b128 v94, v[76:79] offset:27648
	s_waitcnt lgkmcnt(4)
	v_mfma_f32_32x32x16_bf16 v[48:63], v[88:91], v[80:83], v[48:63]
	s_waitcnt lgkmcnt(2)
	v_mfma_f32_32x32x16_bf16 v[32:47], v[104:107], v[80:83], v[32:47]
	v_mfma_f32_32x32x16_bf16 v[16:31], v[88:91], v[84:87], v[16:31]
	v_mfma_f32_32x32x16_bf16 v[0:15], v[104:107], v[84:87], v[0:15]
	ds_read_b128 v[72:75], v95 offset:64
	ds_read_b128 v[76:79], v95 offset:4672
	ds_read_b64_tr_b16 v[80:81], v103 offset:36864
	ds_read_b64_tr_b16 v[82:83], v103 offset:39168
	ds_read_b64_tr_b16 v[84:85], v103 offset:36928
	ds_read_b64_tr_b16 v[86:87], v103 offset:39232
	s_waitcnt vmcnt(1)
	ds_write_b128 v94, v[68:71] offset:36864
	s_waitcnt lgkmcnt(3)
	v_mfma_f32_32x32x16_bf16 v[48:63], v[80:83], v[72:75], v[48:63]
	s_waitcnt lgkmcnt(1)
	v_mfma_f32_32x32x16_bf16 v[32:47], v[84:87], v[72:75], v[32:47]
	v_mfma_f32_32x32x16_bf16 v[16:31], v[80:83], v[76:79], v[16:31]
	v_mfma_f32_32x32x16_bf16 v[0:15], v[84:87], v[76:79], v[0:15]
	ds_read_b128 v[68:71], v95 offset:96
	ds_read_b128 v[72:75], v95 offset:4704
	ds_read_b64_tr_b16 v[76:77], v103 offset:46080
	ds_read_b64_tr_b16 v[78:79], v103 offset:48384
	ds_read_b64_tr_b16 v[80:81], v103 offset:46144
	ds_read_b64_tr_b16 v[82:83], v103 offset:48448
	v_add3_u32 v84, s1, v93, v100
	s_waitcnt vmcnt(0)
	ds_write_b128 v94, v[64:67] offset:46080
	s_waitcnt lgkmcnt(0)
	s_barrier
; DI f32x16 mfma32(bf16x8 a, bf16x8 b, f32x16 c) { return __builtin_amdgcn_mfma_f32_32x32x16_bf16(a, b, c, 0, 0, 0); }
; DI s16x4 tr_read(const char* p) { bfx4 r = __builtin_amdgcn_ds_read_tr16_b64_v4bf16((LDS_AS bfx4*)p); return __builtin_bit_cast(s16x4, r); }
; DI bf16x8 cat8(s16x4 lo, s16x4 hi) { return __builtin_shufflevector(lo, hi, 0, 1, 2, 3, 4, 5, 6, 7); }
; template <int BM, class Epi>
; DI void gemm_tile(const bf16_t* __restrict__ A, int lda, const bf16_t* __restrict__ B, int ldb, int K, int row0, int col0, const Epi& epi, char* smem) {
;     ...
; #pragma unroll
;         for (int s = 0; s < 4; ++s) {
;             bf16x8 xf[MI], wf[2];
; #pragma unroll
;             for (int mi = 0; mi < MI; ++mi) xf[mi] = *(const bf16x8*)(cur + xoff + mi * 32 * GA_S + s * 32);
; #pragma unroll
;             for (int ni = 0; ni < 2; ++ni) {
;                 const char* wp = cur + woff + s * 16 * GB_S + ni * 64;
;                 wf[ni] = cat8(tr_read(wp), tr_read(wp + 4 * GB_S));
;             }
; #pragma unroll
;             for (int mi = 0; mi < MI; ++mi)
; #pragma unroll
;                 for (int ni = 0; ni < 2; ++ni) acc[mi][ni] = mfma32(wf[ni], xf[mi], acc[mi][ni]);
	v_add3_u32 v85, s1, v101, v102
	v_mfma_f32_32x32x16_bf16 v[48:63], v[76:79], v[68:71], v[48:63]
	v_mfma_f32_32x32x16_bf16 v[32:47], v[80:83], v[68:71], v[32:47]
	v_mfma_f32_32x32x16_bf16 v[16:31], v[76:79], v[72:75], v[16:31]
	v_mfma_f32_32x32x16_bf16 v[0:15], v[80:83], v[72:75], v[0:15]
	ds_read_b128 v[64:67], v84 offset:4608
	ds_read_b64_tr_b16 v[68:69], v85 offset:18432
	ds_read_b64_tr_b16 v[70:71], v85 offset:20736
	ds_read_b64_tr_b16 v[72:73], v85 offset:18496
	ds_read_b64_tr_b16 v[74:75], v85 offset:20800
	ds_read_b128 v[76:79], v84
	ds_read_b128 v[80:83], v84 offset:32
	s_waitcnt lgkmcnt(1)
	v_mfma_f32_32x32x16_bf16 v[48:63], v[68:71], v[76:79], v[48:63]
	v_mfma_f32_32x32x16_bf16 v[32:47], v[72:75], v[76:79], v[32:47]
	v_mfma_f32_32x32x16_bf16 v[16:31], v[68:71], v[64:67], v[16:31]
	v_mfma_f32_32x32x16_bf16 v[0:15], v[72:75], v[64:67], v[0:15]
	ds_read_b128 v[64:67], v84 offset:4640
	ds_read_b64_tr_b16 v[68:69], v85 offset:27648
	ds_read_b64_tr_b16 v[70:71], v85 offset:29952
	ds_read_b64_tr_b16 v[72:73], v85 offset:27712
	ds_read_b64_tr_b16 v[74:75], v85 offset:30016
	s_waitcnt lgkmcnt(2)
	v_mfma_f32_32x32x16_bf16 v[48:63], v[68:71], v[80:83], v[48:63]
	s_waitcnt lgkmcnt(0)
	v_mfma_f32_32x32x16_bf16 v[32:47], v[72:75], v[80:83], v[32:47]
	v_mfma_f32_32x32x16_bf16 v[16:31], v[68:71], v[64:67], v[16:31]
	v_mfma_f32_32x32x16_bf16 v[0:15], v[72:75], v[64:67], v[0:15]
	ds_read_b128 v[64:67], v84 offset:64
	ds_read_b128 v[68:71], v84 offset:4672
	ds_read_b64_tr_b16 v[72:73], v85 offset:36864
	ds_read_b64_tr_b16 v[74:75], v85 offset:39168
	ds_read_b64_tr_b16 v[76:77], v85 offset:36928
	ds_read_b64_tr_b16 v[78:79], v85 offset:39232
	s_waitcnt lgkmcnt(2)
	v_mfma_f32_32x32x16_bf16 v[48:63], v[72:75], v[64:67], v[48:63]
	s_waitcnt lgkmcnt(0)
	v_mfma_f32_32x32x16_bf16 v[32:47], v[76:79], v[64:67], v[32:47]
	v_mfma_f32_32x32x16_bf16 v[16:31], v[72:75], v[68:71], v[16:31]
	v_mfma_f32_32x32x16_bf16 v[0:15], v[76:79], v[68:71], v[0:15]
	ds_read_b128 v[64:67], v84 offset:96
	ds_read_b128 v[68:71], v84 offset:4704
	ds_read_b64_tr_b16 v[72:73], v85 offset:46080
	ds_read_b64_tr_b16 v[74:75], v85 offset:48384
	ds_read_b64_tr_b16 v[76:77], v85 offset:46144
	ds_read_b64_tr_b16 v[78:79], v85 offset:48448
	s_waitcnt lgkmcnt(0)
	s_barrier
; DI unsigned pk2(float a, float b) { f32x2 v = {a, b}; bfx2 r = __builtin_convertvector(v, bfx2); return __builtin_bit_cast(unsigned, r); }
; template <int BM, class Epi>
; DI void gemm_tile(const bf16_t* __restrict__ A, int lda, const bf16_t* __restrict__ B, int ldb, int K, int row0, int col0, const Epi& epi, char* smem) {
;     ...
; #pragma unroll
;     for (int mi = 0; mi < MI; ++mi) epi(acc[mi][0], acc[mi][1], row0 + wm * (BM / 2) + mi * 32 + l31, col0 + wn * 64, hh);
;     DI void operator()(const f32x16& a0, const f32x16& a1, int row, int cbase, int hh) const {
;         const int s = row < RL ? (row >> 13) : 4;
;         const float* gp = gate + s * 9216;
;         bf16_t* yp = Y + (size_t)row * 1024;
; #pragma unroll
;         for (int ni = 0; ni < 2; ++ni)
; #pragma unroll
;             for (int q4 = 0; q4 < 4; ++q4) {
;                 const int c = cbase + ni * 32 + 8 * q4 + 4 * hh;
;                 const f32x4 g = *(const f32x4*)(gp + c);
;                 const f32x16& v = ni ? a1 : a0;
;                 u32x2 w; w.x = pk2(coef * g[0] * v[4 * q4], coef * g[1] * v[4 * q4 + 1]); w.y = pk2(coef * g[2] * v[4 * q4 + 2], coef * g[3] * v[4 * q4 + 3]);
;                 *(u32x2*)(yp + c) = w;
;             }
;     }
	v_mfma_f32_32x32x16_bf16 v[48:63], v[72:75], v[64:67], v[48:63]
	v_mfma_f32_32x32x16_bf16 v[32:47], v[76:79], v[64:67], v[32:47]
	v_or_b32_e32 v64, s11, v97
	v_and_b32_e32 v65, 0xc0, v96
	v_add_u32_e32 v64, v64, v99
	v_lshlrev_b32_e32 v66, 2, v98
	v_mfma_f32_32x32x16_bf16 v[16:31], v[72:75], v[68:71], v[16:31]
	v_or3_b32 v72, v66, v65, s0
	v_min_i32_e32 v65, 0x8000, v64
	v_ashrrev_i32_e32 v65, 13, v65
	v_mul_i32_i24_e32 v66, 0x2400, v65
	v_ashrrev_i32_e32 v67, 31, v66
	v_ashrrev_i32_e32 v65, 31, v64
	v_readlane_b32 s0, v253, 3
	v_mfma_f32_32x32x16_bf16 v[0:15], v[76:79], v[68:71], v[0:15]
	v_ashrrev_i32_e32 v73, 31, v72
	v_lshl_add_u64 v[68:69], v[66:67], 2, s[4:5]
	v_lshlrev_b64 v[66:67], 11, v[64:65]
	v_readlane_b32 s1, v253, 4
	s_nop 1
	v_lshl_add_u64 v[74:75], s[0:1], 0, v[66:67]
	v_lshlrev_b64 v[66:67], 2, v[72:73]
	v_lshl_add_u64 v[76:77], v[68:69], 0, v[66:67]
	global_load_dwordx4 v[228:231], v[76:77], off
	global_load_dwordx4 v[232:235], v[76:77], off offset:32
	global_load_dwordx4 v[236:239], v[76:77], off offset:64
	global_load_dwordx4 v[240:243], v[76:77], off offset:96
	s_waitcnt vmcnt(0)
	v_pk_mul_f32 v[48:49], v[48:49], v[228:229]
	s_nop 0
	v_cvt_pk_bf16_f32 v68, v48, v49
	v_pk_mul_f32 v[48:49], v[50:51], v[230:231]
	s_nop 0
	v_cvt_pk_bf16_f32 v69, v48, v49
	v_lshlrev_b64 v[48:49], 1, v[72:73]
	v_lshl_add_u64 v[72:73], v[74:75], 0, v[48:49]
	global_store_dwordx2 v[72:73], v[68:69], off
	v_pk_mul_f32 v[50:51], v[52:53], v[232:233]
	v_pk_mul_f32 v[52:53], v[54:55], v[234:235]
	v_cvt_pk_bf16_f32 v50, v50, v51
	v_cvt_pk_bf16_f32 v51, v52, v53
	global_store_dwordx2 v[72:73], v[50:51], off offset:16
	v_pk_mul_f32 v[50:51], v[56:57], v[236:237]
	v_pk_mul_f32 v[52:53], v[58:59], v[238:239]
	v_cvt_pk_bf16_f32 v50, v50, v51
	v_cvt_pk_bf16_f32 v51, v52, v53
	global_store_dwordx2 v[72:73], v[50:51], off offset:32
	v_pk_mul_f32 v[50:51], v[60:61], v[240:241]
	v_pk_mul_f32 v[52:53], v[62:63], v[242:243]
	v_cvt_pk_bf16_f32 v50, v50, v51
	v_cvt_pk_bf16_f32 v51, v52, v53
	global_store_dwordx2 v[72:73], v[50:51], off offset:48
	global_load_dwordx4 v[228:231], v[76:77], off offset:128
	global_load_dwordx4 v[232:235], v[76:77], off offset:160
	global_load_dwordx4 v[236:239], v[76:77], off offset:192
	global_load_dwordx4 v[240:243], v[76:77], off offset:224
	s_waitcnt vmcnt(0)
	v_pk_mul_f32 v[32:33], v[32:33], v[228:229]
	v_pk_mul_f32 v[34:35], v[34:35], v[230:231]
	v_cvt_pk_bf16_f32 v32, v32, v33
	v_cvt_pk_bf16_f32 v33, v34, v35
	global_store_dwordx2 v[72:73], v[32:33], off offset:64
	v_pk_mul_f32 v[32:33], v[36:37], v[232:233]
	v_pk_mul_f32 v[34:35], v[38:39], v[234:235]
	v_cvt_pk_bf16_f32 v32, v32, v33
	v_cvt_pk_bf16_f32 v33, v34, v35
	global_store_dwordx2 v[72:73], v[32:33], off offset:80
	v_pk_mul_f32 v[32:33], v[40:41], v[236:237]
	v_pk_mul_f32 v[34:35], v[42:43], v[238:239]
	v_cvt_pk_bf16_f32 v32, v32, v33
	v_cvt_pk_bf16_f32 v33, v34, v35
	global_store_dwordx2 v[72:73], v[32:33], off offset:96
	v_pk_mul_f32 v[32:33], v[44:45], v[240:241]
	v_pk_mul_f32 v[34:35], v[46:47], v[242:243]
	v_cvt_pk_bf16_f32 v32, v32, v33
	v_cvt_pk_bf16_f32 v33, v34, v35
	global_store_dwordx2 v[72:73], v[32:33], off offset:112
	v_or_b32_e32 v32, 32, v64
	v_min_i32_e32 v33, 0x8000, v32
	v_ashrrev_i32_e32 v33, 13, v33
	v_mul_i32_i24_e32 v34, 0x2400, v33
	v_ashrrev_i32_e32 v35, 31, v34
	v_lshl_add_u64 v[34:35], v[34:35], 2, s[4:5]
	v_ashrrev_i32_e32 v33, 31, v32
	v_lshlrev_b64 v[32:33], 11, v[32:33]
	v_lshl_add_u64 v[38:39], v[34:35], 0, v[66:67]
	v_lshl_add_u64 v[36:37], s[0:1], 0, v[32:33]
	global_load_dwordx4 v[228:231], v[38:39], off
	global_load_dwordx4 v[232:235], v[38:39], off offset:32
	global_load_dwordx4 v[236:239], v[38:39], off offset:64
	global_load_dwordx4 v[240:243], v[38:39], off offset:96
	s_waitcnt vmcnt(0)
	v_pk_mul_f32 v[16:17], v[16:17], v[228:229]
	v_pk_mul_f32 v[18:19], v[18:19], v[230:231]
	v_cvt_pk_bf16_f32 v16, v16, v17
	v_cvt_pk_bf16_f32 v17, v18, v19
	v_lshl_add_u64 v[32:33], v[36:37], 0, v[48:49]
	global_store_dwordx2 v[32:33], v[16:17], off
	v_pk_mul_f32 v[16:17], v[20:21], v[232:233]
	v_pk_mul_f32 v[18:19], v[22:23], v[234:235]
	v_cvt_pk_bf16_f32 v16, v16, v17
	v_cvt_pk_bf16_f32 v17, v18, v19
	global_store_dwordx2 v[32:33], v[16:17], off offset:16
	v_pk_mul_f32 v[16:17], v[24:25], v[236:237]
	v_pk_mul_f32 v[18:19], v[26:27], v[238:239]
	v_cvt_pk_bf16_f32 v16, v16, v17
	v_cvt_pk_bf16_f32 v17, v18, v19
	global_store_dwordx2 v[32:33], v[16:17], off offset:32
	v_pk_mul_f32 v[16:17], v[28:29], v[240:241]
	v_pk_mul_f32 v[18:19], v[30:31], v[242:243]
	v_cvt_pk_bf16_f32 v16, v16, v17
	v_cvt_pk_bf16_f32 v17, v18, v19
	global_store_dwordx2 v[32:33], v[16:17], off offset:48
	global_load_dwordx4 v[228:231], v[38:39], off offset:128
	global_load_dwordx4 v[232:235], v[38:39], off offset:160
	global_load_dwordx4 v[236:239], v[38:39], off offset:192
	global_load_dwordx4 v[240:243], v[38:39], off offset:224
	s_waitcnt vmcnt(0)
	v_pk_mul_f32 v[0:1], v[0:1], v[228:229]
	v_pk_mul_f32 v[2:3], v[2:3], v[230:231]
	v_cvt_pk_bf16_f32 v0, v0, v1
	v_cvt_pk_bf16_f32 v1, v2, v3
	global_store_dwordx2 v[32:33], v[0:1], off offset:64
	v_pk_mul_f32 v[0:1], v[4:5], v[232:233]
	v_pk_mul_f32 v[2:3], v[6:7], v[234:235]
	v_cvt_pk_bf16_f32 v0, v0, v1
	v_cvt_pk_bf16_f32 v1, v2, v3
	global_store_dwordx2 v[32:33], v[0:1], off offset:80
	v_pk_mul_f32 v[0:1], v[8:9], v[236:237]
	v_pk_mul_f32 v[2:3], v[10:11], v[238:239]
	v_cvt_pk_bf16_f32 v0, v0, v1
	v_cvt_pk_bf16_f32 v1, v2, v3
	global_store_dwordx2 v[32:33], v[0:1], off offset:96
	v_pk_mul_f32 v[0:1], v[12:13], v[240:241]
	v_pk_mul_f32 v[2:3], v[14:15], v[242:243]
	v_cvt_pk_bf16_f32 v0, v0, v1
	v_cvt_pk_bf16_f32 v1, v2, v3
	global_store_dwordx2 v[32:33], v[0:1], off offset:112
	s_cmp_ge_i32 s12, s10
	s_cbranch_scc0 .LBB0_90
